# LDS-DMA loads use SGPR-base + 32-bit VGPR offset form (fewer 64-bit VALU adds in the loader path)
# speedup vs baseline: 1.0389x; 1.0009x over previous
.LBB0_384:
	s_add_u32 s54, s42, 0xfffd0080
	s_addc_u32 s55, s43, -1
	s_add_i32 s70, 0, 0x10000
	v_add_u32_e32 v96, s70, v157
	ds_read_b128 v[160:163], v96
	ds_read_b128 v[164:167], v96 offset:1024
	ds_read_b128 v[168:171], v96 offset:2048
	ds_read_b128 v[172:175], v96 offset:3072
	s_cmp_eq_u32 s69, 12
	s_cselect_b32 s57, s51, s55
	s_cselect_b32 s56, s50, s54
	s_cselect_b32 s55, s49, s68
	s_cselect_b32 s54, s66, s67
	s_add_i32 m0, s28, 0xc000
	ds_read_b128 v[182:185], v159
	ds_read_b128 v[186:189], v159 offset:1024
	ds_read_b128 v[190:193], v159 offset:2048
	ds_read_b128 v[194:197], v159 offset:3072
	ds_read_b128 v[198:201], v159 offset:4096
	ds_read_b128 v[224:227], v159 offset:5120
	global_load_lds_dwordx4 v150, s[42:43]
	s_add_i32 m0, s28, 0xe000
	s_mov_b64 exec, s[98:99]
	global_load_lds_dwordx4 v152, s[42:43]
	s_mov_b64 exec, -1
	s_waitcnt lgkmcnt(8)
	s_setprio 1
	s_barrier
	s_waitcnt lgkmcnt(0)
	v_mfma_f32_16x16x32_bf16 v[134:137], v[160:163], v[182:185], v[134:137]
	v_mfma_f32_16x16x32_bf16 v[130:133], v[168:171], v[182:185], v[130:133]
	v_mfma_f32_16x16x32_bf16 v[118:121], v[160:163], v[190:193], v[118:121]
	v_mfma_f32_16x16x32_bf16 v[114:117], v[168:171], v[190:193], v[114:117]
	v_mfma_f32_16x16x32_bf16 v[102:105], v[160:163], v[198:201], v[102:105]
	v_mfma_f32_16x16x32_bf16 v[98:101], v[168:171], v[198:201], v[98:101]
	v_mfma_f32_16x16x32_bf16 v[134:137], v[164:167], v[186:189], v[134:137]
	v_mfma_f32_16x16x32_bf16 v[130:133], v[172:175], v[186:189], v[130:133]
	v_mfma_f32_16x16x32_bf16 v[118:121], v[164:167], v[194:197], v[118:121]
	v_mfma_f32_16x16x32_bf16 v[114:117], v[172:175], v[194:197], v[114:117]
	v_mfma_f32_16x16x32_bf16 v[102:105], v[164:167], v[224:227], v[102:105]
	v_mfma_f32_16x16x32_bf16 v[98:101], v[172:175], v[224:227], v[98:101]
	s_barrier
	s_setprio 0
	s_add_i32 s72, 0, 0x14000
	s_add_i32 s70, s70, s18
	v_add_u32_e32 v96, s72, v157
	v_lshl_add_u64 v[154:155], s[54:55], 0, v[142:143]
	s_mov_b32 m0, s70
	ds_read_b128 v[228:231], v96
	ds_read_b128 v[232:235], v96 offset:1024
	ds_read_b128 v[236:239], v96 offset:2048
	ds_read_b128 v[240:243], v96 offset:3072
	global_load_lds_dwordx4 v142, s[54:55]
	v_lshl_add_u64 v[176:177], s[54:55], 0, v[138:139]
	s_add_i32 m0, s70, 0x2000
	s_nop 0
	global_load_lds_dwordx4 v138, s[54:55]
	s_setprio 1
	s_barrier
	s_waitcnt lgkmcnt(0)
	v_mfma_f32_16x16x32_bf16 v[126:129], v[228:231], v[182:185], v[126:129]
	v_mfma_f32_16x16x32_bf16 v[122:125], v[236:239], v[182:185], v[122:125]
	v_mfma_f32_16x16x32_bf16 v[110:113], v[228:231], v[190:193], v[110:113]
	s_mov_b32 m0, s28
	v_mfma_f32_16x16x32_bf16 v[106:109], v[236:239], v[190:193], v[106:109]
	v_lshl_add_u64 v[202:203], s[56:57], 0, v[144:145]
	v_mfma_f32_16x16x32_bf16 v[92:95], v[228:231], v[198:201], v[92:95]
	v_mfma_f32_16x16x32_bf16 v[88:91], v[236:239], v[198:201], v[88:91]
	v_mfma_f32_16x16x32_bf16 v[126:129], v[232:235], v[186:189], v[126:129]
	v_mfma_f32_16x16x32_bf16 v[122:125], v[240:243], v[186:189], v[122:125]
	v_mfma_f32_16x16x32_bf16 v[110:113], v[232:235], v[194:197], v[110:113]
	v_mfma_f32_16x16x32_bf16 v[106:109], v[240:243], v[194:197], v[106:109]
	v_mfma_f32_16x16x32_bf16 v[92:95], v[232:235], v[224:227], v[92:95]
	v_mfma_f32_16x16x32_bf16 v[88:91], v[240:243], v[224:227], v[88:91]
	s_barrier
	s_setprio 0
	ds_read_b128 v[182:185], v159 offset:16384
	ds_read_b128 v[186:189], v159 offset:17408
	ds_read_b128 v[190:193], v159 offset:18432
	ds_read_b128 v[194:197], v159 offset:19456
	ds_read_b128 v[198:201], v159 offset:20480
	ds_read_b128 v[224:227], v159 offset:21504
	global_load_lds_dwordx4 v144, s[56:57]
	v_lshl_add_u64 v[244:245], s[56:57], 0, v[140:141]
	s_mov_b32 m0, s37
	s_mov_b64 exec, s[98:99]
	global_load_lds_dwordx4 v140, s[56:57]
	s_mov_b64 exec, -1
	s_setprio 1
	s_barrier
	s_waitcnt lgkmcnt(0)
	v_mfma_f32_16x16x32_bf16 v[84:87], v[160:163], v[182:185], v[84:87]
	v_mfma_f32_16x16x32_bf16 v[80:83], v[168:171], v[182:185], v[80:83]
	v_mfma_f32_16x16x32_bf16 v[68:71], v[160:163], v[190:193], v[68:71]
	v_mfma_f32_16x16x32_bf16 v[64:67], v[168:171], v[190:193], v[64:67]
	v_mfma_f32_16x16x32_bf16 v[28:31], v[160:163], v[198:201], v[28:31]
	v_mfma_f32_16x16x32_bf16 v[24:27], v[168:171], v[198:201], v[24:27]
	v_mfma_f32_16x16x32_bf16 v[84:87], v[164:167], v[186:189], v[84:87]
	v_mfma_f32_16x16x32_bf16 v[80:83], v[172:175], v[186:189], v[80:83]
	v_mfma_f32_16x16x32_bf16 v[68:71], v[164:167], v[194:197], v[68:71]
	v_mfma_f32_16x16x32_bf16 v[64:67], v[172:175], v[194:197], v[64:67]
	v_mfma_f32_16x16x32_bf16 v[28:31], v[164:167], v[224:227], v[28:31]
	v_mfma_f32_16x16x32_bf16 v[24:27], v[172:175], v[224:227], v[24:27]
	s_barrier
	s_setprio 0
	s_add_u32 s70, s54, 0x40000
	s_addc_u32 s71, s55, 0
	s_add_i32 s72, s72, s18
	s_mov_b32 m0, s72
	s_nop 0
	global_load_lds_dwordx4 v142, s[70:71]
	s_add_i32 m0, s72, 0x2000
	s_nop 0
	global_load_lds_dwordx4 v138, s[70:71]
	s_waitcnt vmcnt(6)
	s_setprio 1
	s_barrier
	v_mfma_f32_16x16x32_bf16 v[76:79], v[228:231], v[182:185], v[76:79]
	v_mfma_f32_16x16x32_bf16 v[72:75], v[236:239], v[182:185], v[72:75]
	v_mfma_f32_16x16x32_bf16 v[60:63], v[228:231], v[190:193], v[60:63]
	s_add_i32 s70, 0, 0x18000
	v_mfma_f32_16x16x32_bf16 v[56:59], v[236:239], v[190:193], v[56:59]
	v_add_u32_e32 v96, s70, v157
	v_mfma_f32_16x16x32_bf16 v[20:23], v[228:231], v[198:201], v[20:23]
	v_mfma_f32_16x16x32_bf16 v[16:19], v[236:239], v[198:201], v[16:19]
	v_mfma_f32_16x16x32_bf16 v[76:79], v[232:235], v[186:189], v[76:79]
	v_mfma_f32_16x16x32_bf16 v[72:75], v[240:243], v[186:189], v[72:75]
	v_mfma_f32_16x16x32_bf16 v[60:63], v[232:235], v[194:197], v[60:63]
	v_mfma_f32_16x16x32_bf16 v[56:59], v[240:243], v[194:197], v[56:59]
	v_mfma_f32_16x16x32_bf16 v[20:23], v[232:235], v[224:227], v[20:23]
	v_mfma_f32_16x16x32_bf16 v[16:19], v[240:243], v[224:227], v[16:19]
	s_barrier
	s_setprio 0
	ds_read_b128 v[160:163], v96
	ds_read_b128 v[164:167], v96 offset:1024
	ds_read_b128 v[168:171], v96 offset:2048
	ds_read_b128 v[172:175], v96 offset:3072
	s_add_u32 s56, s56, 0x30000
	s_addc_u32 s57, s57, 0
	s_mov_b32 m0, s58
	ds_read_b128 v[182:185], v159 offset:32768
	ds_read_b128 v[186:189], v159 offset:33792
	ds_read_b128 v[190:193], v159 offset:34816
	ds_read_b128 v[194:197], v159 offset:35840
	ds_read_b128 v[198:201], v159 offset:36864
	ds_read_b128 v[224:227], v159 offset:37888
	global_load_lds_dwordx4 v144, s[56:57]
	s_mov_b32 m0, s59
	s_mov_b64 exec, s[98:99]
	global_load_lds_dwordx4 v140, s[56:57]
	s_mov_b64 exec, -1
	s_waitcnt lgkmcnt(8)
	s_setprio 1
	s_barrier
	s_waitcnt lgkmcnt(0)
	v_mfma_f32_16x16x32_bf16 v[134:137], v[160:163], v[182:185], v[134:137]
	v_mfma_f32_16x16x32_bf16 v[130:133], v[168:171], v[182:185], v[130:133]
	v_mfma_f32_16x16x32_bf16 v[118:121], v[160:163], v[190:193], v[118:121]
	v_mfma_f32_16x16x32_bf16 v[114:117], v[168:171], v[190:193], v[114:117]
	v_mfma_f32_16x16x32_bf16 v[102:105], v[160:163], v[198:201], v[102:105]
	v_mfma_f32_16x16x32_bf16 v[98:101], v[168:171], v[198:201], v[98:101]
	v_mfma_f32_16x16x32_bf16 v[134:137], v[164:167], v[186:189], v[134:137]
	v_mfma_f32_16x16x32_bf16 v[130:133], v[172:175], v[186:189], v[130:133]
	v_mfma_f32_16x16x32_bf16 v[118:121], v[164:167], v[194:197], v[118:121]
	v_mfma_f32_16x16x32_bf16 v[114:117], v[172:175], v[194:197], v[114:117]
	v_mfma_f32_16x16x32_bf16 v[102:105], v[164:167], v[224:227], v[102:105]
	v_mfma_f32_16x16x32_bf16 v[98:101], v[172:175], v[224:227], v[98:101]
	s_barrier
	s_setprio 0
	s_add_i32 s56, 0, 0x1c000
	s_add_i32 s57, s70, s18
	v_add_u32_e32 v96, s56, v157
	v_lshl_add_u64 v[154:155], v[154:155], 0, s[6:7]
	s_mov_b32 m0, s57
	ds_read_b128 v[228:231], v96
	ds_read_b128 v[232:235], v96 offset:1024
	ds_read_b128 v[236:239], v96 offset:2048
	ds_read_b128 v[240:243], v96 offset:3072
	global_load_lds_dwordx4 v[154:155], off
	v_lshl_add_u64 v[154:155], v[176:177], 0, s[6:7]
	s_add_i32 m0, s57, 0x2000
	s_nop 0
	global_load_lds_dwordx4 v[154:155], off
	s_setprio 1
	s_barrier
	s_waitcnt lgkmcnt(0)
	v_mfma_f32_16x16x32_bf16 v[126:129], v[228:231], v[182:185], v[126:129]
	v_mfma_f32_16x16x32_bf16 v[122:125], v[236:239], v[182:185], v[122:125]
	v_mfma_f32_16x16x32_bf16 v[110:113], v[228:231], v[190:193], v[110:113]
	s_mov_b32 m0, s60
	v_mfma_f32_16x16x32_bf16 v[106:109], v[236:239], v[190:193], v[106:109]
	v_lshl_add_u64 v[154:155], v[202:203], 0, s[6:7]
	v_mfma_f32_16x16x32_bf16 v[92:95], v[228:231], v[198:201], v[92:95]
	v_mfma_f32_16x16x32_bf16 v[88:91], v[236:239], v[198:201], v[88:91]
	v_mfma_f32_16x16x32_bf16 v[126:129], v[232:235], v[186:189], v[126:129]
	v_mfma_f32_16x16x32_bf16 v[122:125], v[240:243], v[186:189], v[122:125]
	v_mfma_f32_16x16x32_bf16 v[110:113], v[232:235], v[194:197], v[110:113]
	v_mfma_f32_16x16x32_bf16 v[106:109], v[240:243], v[194:197], v[106:109]
	v_mfma_f32_16x16x32_bf16 v[92:95], v[232:235], v[224:227], v[92:95]
	v_mfma_f32_16x16x32_bf16 v[88:91], v[240:243], v[224:227], v[88:91]
	s_barrier
	s_setprio 0
	ds_read_b128 v[182:185], v159 offset:49152
	ds_read_b128 v[186:189], v159 offset:50176
	ds_read_b128 v[190:193], v159 offset:51200
	ds_read_b128 v[194:197], v159 offset:52224
	ds_read_b128 v[198:201], v159 offset:53248
	ds_read_b128 v[224:227], v159 offset:54272
	global_load_lds_dwordx4 v[154:155], off
	v_lshl_add_u64 v[154:155], v[244:245], 0, s[6:7]
	s_mov_b32 m0, s61
	s_mov_b64 exec, s[98:99]
	global_load_lds_dwordx4 v[154:155], off
	s_mov_b64 exec, -1
	s_setprio 1
	s_barrier
	s_waitcnt lgkmcnt(0)
	v_mfma_f32_16x16x32_bf16 v[84:87], v[160:163], v[182:185], v[84:87]
	v_mfma_f32_16x16x32_bf16 v[80:83], v[168:171], v[182:185], v[80:83]
	v_mfma_f32_16x16x32_bf16 v[68:71], v[160:163], v[190:193], v[68:71]
	v_mfma_f32_16x16x32_bf16 v[64:67], v[168:171], v[190:193], v[64:67]
	v_mfma_f32_16x16x32_bf16 v[28:31], v[160:163], v[198:201], v[28:31]
	v_mfma_f32_16x16x32_bf16 v[24:27], v[168:171], v[198:201], v[24:27]
	v_mfma_f32_16x16x32_bf16 v[84:87], v[164:167], v[186:189], v[84:87]
	v_mfma_f32_16x16x32_bf16 v[80:83], v[172:175], v[186:189], v[80:83]
	v_mfma_f32_16x16x32_bf16 v[68:71], v[164:167], v[194:197], v[68:71]
	v_mfma_f32_16x16x32_bf16 v[64:67], v[172:175], v[194:197], v[64:67]
	v_mfma_f32_16x16x32_bf16 v[28:31], v[164:167], v[224:227], v[28:31]
	v_mfma_f32_16x16x32_bf16 v[24:27], v[172:175], v[224:227], v[24:27]
	s_barrier
	s_setprio 0
	s_add_u32 s54, s54, 0x40080
	s_addc_u32 s55, s55, 0
	s_add_i32 s56, s56, s18
	s_mov_b32 m0, s56
	s_nop 0
	global_load_lds_dwordx4 v142, s[54:55]
	s_add_i32 m0, s56, 0x2000
	s_nop 0
	global_load_lds_dwordx4 v138, s[54:55]
	s_waitcnt vmcnt(6)
	s_setprio 1
	s_barrier
	v_mfma_f32_16x16x32_bf16 v[76:79], v[228:231], v[182:185], v[76:79]
	v_mfma_f32_16x16x32_bf16 v[72:75], v[236:239], v[182:185], v[72:75]
	v_mfma_f32_16x16x32_bf16 v[60:63], v[228:231], v[190:193], v[60:63]
	s_add_i32 s69, s69, 2
	v_mfma_f32_16x16x32_bf16 v[56:59], v[236:239], v[190:193], v[56:59]
	s_add_u32 s42, s42, 0x100
	v_mfma_f32_16x16x32_bf16 v[20:23], v[228:231], v[198:201], v[20:23]
	s_addc_u32 s43, s43, 0
	v_mfma_f32_16x16x32_bf16 v[16:19], v[236:239], v[198:201], v[16:19]
	s_add_u32 s67, s67, 0x100
	v_mfma_f32_16x16x32_bf16 v[76:79], v[232:235], v[186:189], v[76:79]
	s_addc_u32 s68, s68, 0
	v_mfma_f32_16x16x32_bf16 v[72:75], v[240:243], v[186:189], v[72:75]
	s_cmp_gt_u32 s69, 13
	v_mfma_f32_16x16x32_bf16 v[60:63], v[232:235], v[194:197], v[60:63]
	v_mfma_f32_16x16x32_bf16 v[56:59], v[240:243], v[194:197], v[56:59]
	v_mfma_f32_16x16x32_bf16 v[20:23], v[232:235], v[224:227], v[20:23]
	v_mfma_f32_16x16x32_bf16 v[16:19], v[240:243], v[224:227], v[16:19]
	s_barrier
	s_setprio 0
	s_cbranch_scc0 .LBB0_384
	s_waitcnt vmcnt(0)
	v_add_f32_e32 v52, v52, v53
	v_add_f32_e32 v53, v54, v55
	v_add_f32_e32 v52, v52, v53
	v_mov_b32_e32 v53, v52
	s_nop 1
	v_permlane16_swap_b32_e32 v52, v53
	v_add_f32_e32 v52, v52, v53
	v_mov_b32_e32 v53, v52
	s_nop 1
	v_permlane32_swap_b32_e32 v52, v53
	v_add_f32_e32 v52, v52, v53
	v_fmamk_f32 v52, v52, 0x3a800000, v207
	s_mul_i32 s42, s65, 0xc0
	v_rsq_f32_e32 v52, v52
	v_add_f32_e32 v36, v36, v37
	v_add_f32_e32 v37, v38, v39
	s_add_i32 s42, s42, s19
	v_add_f32_e32 v44, v44, v45
	v_add_f32_e32 v45, v46, v47
	v_add_f32_e32 v36, v36, v37
	s_cmpk_lt_u32 s42, 0x2000
	v_add_f32_e32 v44, v44, v45
	v_mov_b32_e32 v37, v36
	v_lshl_or_b32 v154, s64, 8, v158
	s_cselect_b32 s43, 1, 2
	v_or_b32_e32 v160, s42, v156
	v_mov_b32_e32 v45, v44
	v_permlane16_swap_b32_e32 v36, v37
	v_add_f32_e32 v32, v32, v33
	v_add_f32_e32 v33, v34, v35
	v_mov_b64_e32 v[34:35], s[46:47]
	v_mov_b32_e32 v96, s43
	v_permlane16_swap_b32_e32 v44, v45
	v_add_f32_e32 v38, v36, v37
	v_add_f32_e32 v36, v40, v41
	v_add_f32_e32 v37, v42, v43
	v_ashrrev_i32_e32 v155, 31, v154
	v_mad_i64_i32 v[34:35], s[42:43], v160, s25, v[34:35]
	v_pk_fma_f32 v[42:43], v[136:137], v[52:53], v[6:7] op_sel_hi:[1,0,1]
	v_pk_fma_f32 v[40:41], v[134:135], v[52:53], v[4:5] op_sel_hi:[1,0,1]
	v_add_f32_e32 v46, v44, v45
	v_add_f32_e32 v44, v48, v49
	v_add_f32_e32 v45, v50, v51
	v_lshl_add_u64 v[34:35], v[154:155], 1, v[34:35]
	v_pk_fma_f32 v[48:49], v[132:133], v[52:53], v[2:3] op_sel_hi:[1,0,1]
	v_pk_fma_f32 v[50:51], v[130:131], v[52:53], v[0:1] op_sel_hi:[1,0,1]
	v_cvt_pk_bf16_f32 v40, v40, v41
	v_cvt_pk_bf16_f32 v41, v42, v43
	v_add_f32_e32 v44, v44, v45
	v_cvt_pk_bf16_f32 v42, v50, v51
	v_cvt_pk_bf16_f32 v43, v48, v49
	v_add_f32_e32 v36, v36, v37
	v_add_f32_e32 v32, v32, v33
	global_store_dwordx4 v[34:35], v[40:43], off
	v_cmp_lt_i32_e32 vcc, s23, v160
	v_mov_b32_e32 v45, v44
	v_pk_fma_f32 v[42:43], v[128:129], v[52:53], v[14:15] op_sel_hi:[1,0,1]
	v_pk_fma_f32 v[40:41], v[126:127], v[52:53], v[12:13] op_sel_hi:[1,0,1]
	v_mov_b32_e32 v37, v36
	v_mov_b32_e32 v33, v32
	v_pk_fma_f32 v[48:49], v[124:125], v[52:53], v[10:11] op_sel_hi:[1,0,1]
	v_pk_fma_f32 v[50:51], v[122:123], v[52:53], v[8:9] op_sel_hi:[1,0,1]
	v_cvt_pk_bf16_f32 v40, v40, v41
	v_cvt_pk_bf16_f32 v41, v42, v43
	v_cndmask_b32_e32 v96, 0, v96, vcc
	v_cvt_pk_bf16_f32 v42, v50, v51
	v_cvt_pk_bf16_f32 v43, v48, v49
	global_store_dwordx4 v[34:35], v[40:43], off offset:256
	v_add_u32_e32 v34, 16, v160
	v_permlane16_swap_b32_e32 v44, v45
	v_permlane16_swap_b32_e32 v36, v37
	v_permlane16_swap_b32_e32 v32, v33
	v_cmp_gt_u32_e32 vcc, s24, v34
	v_add_f32_e32 v44, v44, v45
	v_add_f32_e32 v36, v36, v37
	v_add_f32_e32 v32, v32, v33
	v_cndmask_b32_e64 v35, 2, 1, vcc
	v_cmp_lt_i32_e32 vcc, s26, v160
	v_mov_b32_e32 v47, v46
	v_mov_b32_e32 v45, v44
	v_mov_b32_e32 v39, v38
	v_mov_b32_e32 v37, v36
	v_mov_b32_e32 v33, v32
	v_cndmask_b32_e32 v35, 0, v35, vcc
	v_permlane32_swap_b32_e32 v46, v47
	v_permlane32_swap_b32_e32 v44, v45
	v_permlane32_swap_b32_e32 v38, v39
	v_permlane32_swap_b32_e32 v36, v37
	v_permlane32_swap_b32_e32 v32, v33
	v_cmp_ne_u32_e32 vcc, v35, v96
	s_and_saveexec_b64 s[42:43], vcc
	s_cbranch_execz .LBB0_387
	v_mul_u32_u24_e32 v0, 0x7600, v35
	v_lshlrev_b32_e32 v96, 2, v0
	v_lshl_add_u64 v[0:1], s[44:45], 0, v[96:97]
	v_lshl_add_u64 v[12:13], v[154:155], 2, v[0:1]
	global_load_dwordx4 v[0:3], v[12:13], off offset:16
	global_load_dwordx4 v[4:7], v[12:13], off
	global_load_dwordx4 v[8:11], v[12:13], off offset:528
	s_nop 0
	global_load_dwordx4 v[12:15], v[12:13], off offset:512
	v_mov_b32_e32 v96, v35

.LBB0_465:
	s_add_u32 s58, s42, 0xfffd0080
	s_addc_u32 s59, s43, -1
	s_add_i32 s72, 0, 0x10000
	v_add_u32_e32 v96, s72, v163
	ds_read_b128 v[154:157], v96
	ds_read_b128 v[170:173], v96 offset:1024
	ds_read_b128 v[174:177], v96 offset:2048
	ds_read_b128 v[182:185], v96 offset:3072
	s_cmp_eq_u32 s71, 12
	s_cselect_b32 s61, s53, s59
	s_cselect_b32 s60, s52, s58
	s_cselect_b32 s59, s51, s70
	s_cselect_b32 s58, s68, s69
	s_add_i32 m0, s27, 0xc000
	ds_read_b128 v[186:189], v168
	ds_read_b128 v[190:193], v168 offset:1024
	ds_read_b128 v[194:197], v168 offset:2048
	ds_read_b128 v[198:201], v168 offset:3072
	ds_read_b128 v[224:227], v168 offset:4096
	ds_read_b128 v[228:231], v168 offset:5120
	global_load_lds_dwordx4 v150, s[42:43]
	s_add_i32 m0, s27, 0xe000
	s_mov_b64 exec, s[98:99]
	global_load_lds_dwordx4 v152, s[42:43]
	s_mov_b64 exec, -1
	s_waitcnt lgkmcnt(8)
	s_setprio 1
	s_barrier
	s_waitcnt lgkmcnt(0)
	v_mfma_f32_16x16x32_bf16 v[134:137], v[154:157], v[186:189], v[134:137]
	v_mfma_f32_16x16x32_bf16 v[130:133], v[174:177], v[186:189], v[130:133]
	v_mfma_f32_16x16x32_bf16 v[92:95], v[154:157], v[194:197], v[92:95]
	v_mfma_f32_16x16x32_bf16 v[88:91], v[174:177], v[194:197], v[88:91]
	v_mfma_f32_16x16x32_bf16 v[76:79], v[154:157], v[224:227], v[76:79]
	v_mfma_f32_16x16x32_bf16 v[72:75], v[174:177], v[224:227], v[72:75]
	v_mfma_f32_16x16x32_bf16 v[134:137], v[170:173], v[190:193], v[134:137]
	v_mfma_f32_16x16x32_bf16 v[130:133], v[182:185], v[190:193], v[130:133]
	v_mfma_f32_16x16x32_bf16 v[92:95], v[170:173], v[198:201], v[92:95]
	v_mfma_f32_16x16x32_bf16 v[88:91], v[182:185], v[198:201], v[88:91]
	v_mfma_f32_16x16x32_bf16 v[76:79], v[170:173], v[228:231], v[76:79]
	v_mfma_f32_16x16x32_bf16 v[72:75], v[182:185], v[228:231], v[72:75]
	s_barrier
	s_setprio 0
	s_add_i32 s80, 0, 0x14000
	s_add_i32 s72, s72, s18
	v_add_u32_e32 v96, s80, v163
	v_lshl_add_u64 v[160:161], s[58:59], 0, v[140:141]
	s_mov_b32 m0, s72
	ds_read_b128 v[232:235], v96
	ds_read_b128 v[236:239], v96 offset:1024
	ds_read_b128 v[240:243], v96 offset:2048
	ds_read_b128 v[244:247], v96 offset:3072
	global_load_lds_dwordx4 v140, s[58:59]
	v_lshl_add_u64 v[164:165], s[58:59], 0, v[144:145]
	s_add_i32 m0, s72, 0x2000
	s_nop 0
	global_load_lds_dwordx4 v144, s[58:59]
	s_setprio 1
	s_barrier
	s_waitcnt lgkmcnt(0)
	v_mfma_f32_16x16x32_bf16 v[110:113], v[232:235], v[186:189], v[110:113]
	v_mfma_f32_16x16x32_bf16 v[98:101], v[240:243], v[186:189], v[98:101]
	v_mfma_f32_16x16x32_bf16 v[84:87], v[232:235], v[194:197], v[84:87]
	s_mov_b32 m0, s27
	v_mfma_f32_16x16x32_bf16 v[80:83], v[240:243], v[194:197], v[80:83]
	v_lshl_add_u64 v[202:203], s[60:61], 0, v[138:139]
	v_mfma_f32_16x16x32_bf16 v[68:71], v[232:235], v[224:227], v[68:71]
	v_mfma_f32_16x16x32_bf16 v[64:67], v[240:243], v[224:227], v[64:67]
	v_mfma_f32_16x16x32_bf16 v[110:113], v[236:239], v[190:193], v[110:113]
	v_mfma_f32_16x16x32_bf16 v[98:101], v[244:247], v[190:193], v[98:101]
	v_mfma_f32_16x16x32_bf16 v[84:87], v[236:239], v[198:201], v[84:87]
	v_mfma_f32_16x16x32_bf16 v[80:83], v[244:247], v[198:201], v[80:83]
	v_mfma_f32_16x16x32_bf16 v[68:71], v[236:239], v[228:231], v[68:71]
	v_mfma_f32_16x16x32_bf16 v[64:67], v[244:247], v[228:231], v[64:67]
	s_barrier
	s_setprio 0
	ds_read_b128 v[186:189], v168 offset:16384
	ds_read_b128 v[190:193], v168 offset:17408
	ds_read_b128 v[194:197], v168 offset:18432
	ds_read_b128 v[198:201], v168 offset:19456
	ds_read_b128 v[224:227], v168 offset:20480
	ds_read_b128 v[228:231], v168 offset:21504
	global_load_lds_dwordx4 v138, s[60:61]
	v_lshl_add_u64 v[248:249], s[60:61], 0, v[142:143]
	s_mov_b32 m0, s28
	s_mov_b64 exec, s[98:99]
	global_load_lds_dwordx4 v142, s[60:61]
	s_mov_b64 exec, -1
	s_setprio 1
	s_barrier
	s_waitcnt lgkmcnt(0)
	v_mfma_f32_16x16x32_bf16 v[60:63], v[154:157], v[186:189], v[60:63]
	v_mfma_f32_16x16x32_bf16 v[56:59], v[174:177], v[186:189], v[56:59]
	v_mfma_f32_16x16x32_bf16 v[44:47], v[154:157], v[194:197], v[44:47]
	v_mfma_f32_16x16x32_bf16 v[40:43], v[174:177], v[194:197], v[40:43]
	v_mfma_f32_16x16x32_bf16 v[28:31], v[154:157], v[224:227], v[28:31]
	v_mfma_f32_16x16x32_bf16 v[24:27], v[174:177], v[224:227], v[24:27]
	v_mfma_f32_16x16x32_bf16 v[60:63], v[170:173], v[190:193], v[60:63]
	v_mfma_f32_16x16x32_bf16 v[56:59], v[182:185], v[190:193], v[56:59]
	v_mfma_f32_16x16x32_bf16 v[44:47], v[170:173], v[198:201], v[44:47]
	v_mfma_f32_16x16x32_bf16 v[40:43], v[182:185], v[198:201], v[40:43]
	v_mfma_f32_16x16x32_bf16 v[28:31], v[170:173], v[228:231], v[28:31]
	v_mfma_f32_16x16x32_bf16 v[24:27], v[182:185], v[228:231], v[24:27]
	s_barrier
	s_setprio 0
	s_add_u32 s78, s58, 0x40000
	s_addc_u32 s79, s59, 0
	s_add_i32 s72, s80, s18
	s_mov_b32 m0, s72
	s_nop 0
	global_load_lds_dwordx4 v140, s[78:79]
	s_add_i32 m0, s72, 0x2000
	s_nop 0
	global_load_lds_dwordx4 v144, s[78:79]
	s_waitcnt vmcnt(6)
	s_setprio 1
	s_barrier
	v_mfma_f32_16x16x32_bf16 v[52:55], v[232:235], v[186:189], v[52:55]
	v_mfma_f32_16x16x32_bf16 v[48:51], v[240:243], v[186:189], v[48:51]
	v_mfma_f32_16x16x32_bf16 v[36:39], v[232:235], v[194:197], v[36:39]
	s_add_i32 s72, 0, 0x18000
	v_mfma_f32_16x16x32_bf16 v[32:35], v[240:243], v[194:197], v[32:35]
	v_add_u32_e32 v96, s72, v163
	v_mfma_f32_16x16x32_bf16 v[20:23], v[232:235], v[224:227], v[20:23]
	v_mfma_f32_16x16x32_bf16 v[16:19], v[240:243], v[224:227], v[16:19]
	v_mfma_f32_16x16x32_bf16 v[52:55], v[236:239], v[190:193], v[52:55]
	v_mfma_f32_16x16x32_bf16 v[48:51], v[244:247], v[190:193], v[48:51]
	v_mfma_f32_16x16x32_bf16 v[36:39], v[236:239], v[198:201], v[36:39]
	v_mfma_f32_16x16x32_bf16 v[32:35], v[244:247], v[198:201], v[32:35]
	v_mfma_f32_16x16x32_bf16 v[20:23], v[236:239], v[228:231], v[20:23]
	v_mfma_f32_16x16x32_bf16 v[16:19], v[244:247], v[228:231], v[16:19]
	s_barrier
	s_setprio 0
	ds_read_b128 v[154:157], v96
	ds_read_b128 v[170:173], v96 offset:1024
	ds_read_b128 v[174:177], v96 offset:2048
	ds_read_b128 v[182:185], v96 offset:3072
	s_add_u32 s60, s60, 0x30000
	s_addc_u32 s61, s61, 0
	s_mov_b32 m0, s37
	ds_read_b128 v[186:189], v168 offset:32768
	ds_read_b128 v[190:193], v168 offset:33792
	ds_read_b128 v[194:197], v168 offset:34816
	ds_read_b128 v[198:201], v168 offset:35840
	ds_read_b128 v[224:227], v168 offset:36864
	ds_read_b128 v[228:231], v168 offset:37888
	global_load_lds_dwordx4 v138, s[60:61]
	s_mov_b32 m0, s57
	s_mov_b64 exec, s[98:99]
	global_load_lds_dwordx4 v142, s[60:61]
	s_mov_b64 exec, -1
	s_waitcnt lgkmcnt(8)
	s_setprio 1
	s_barrier
	s_waitcnt lgkmcnt(0)
	v_mfma_f32_16x16x32_bf16 v[134:137], v[154:157], v[186:189], v[134:137]
	v_mfma_f32_16x16x32_bf16 v[130:133], v[174:177], v[186:189], v[130:133]
	v_mfma_f32_16x16x32_bf16 v[92:95], v[154:157], v[194:197], v[92:95]
	v_mfma_f32_16x16x32_bf16 v[88:91], v[174:177], v[194:197], v[88:91]
	v_mfma_f32_16x16x32_bf16 v[76:79], v[154:157], v[224:227], v[76:79]
	v_mfma_f32_16x16x32_bf16 v[72:75], v[174:177], v[224:227], v[72:75]
	v_mfma_f32_16x16x32_bf16 v[134:137], v[170:173], v[190:193], v[134:137]
	v_mfma_f32_16x16x32_bf16 v[130:133], v[182:185], v[190:193], v[130:133]
	v_mfma_f32_16x16x32_bf16 v[92:95], v[170:173], v[198:201], v[92:95]
	v_mfma_f32_16x16x32_bf16 v[88:91], v[182:185], v[198:201], v[88:91]
	v_mfma_f32_16x16x32_bf16 v[76:79], v[170:173], v[228:231], v[76:79]
	v_mfma_f32_16x16x32_bf16 v[72:75], v[182:185], v[228:231], v[72:75]
	s_barrier
	s_setprio 0
	s_add_i32 s60, 0, 0x1c000
	s_add_i32 s61, s72, s18
	v_add_u32_e32 v96, s60, v163
	v_lshl_add_u64 v[160:161], v[160:161], 0, s[6:7]
	s_mov_b32 m0, s61
	ds_read_b128 v[232:235], v96
	ds_read_b128 v[236:239], v96 offset:1024
	ds_read_b128 v[240:243], v96 offset:2048
	ds_read_b128 v[244:247], v96 offset:3072
	global_load_lds_dwordx4 v[160:161], off
	v_lshl_add_u64 v[160:161], v[164:165], 0, s[6:7]
	s_add_i32 m0, s61, 0x2000
	s_nop 0
	global_load_lds_dwordx4 v[160:161], off
	s_setprio 1
	s_barrier
	s_waitcnt lgkmcnt(0)
	v_mfma_f32_16x16x32_bf16 v[110:113], v[232:235], v[186:189], v[110:113]
	v_mfma_f32_16x16x32_bf16 v[98:101], v[240:243], v[186:189], v[98:101]
	v_mfma_f32_16x16x32_bf16 v[84:87], v[232:235], v[194:197], v[84:87]
	s_mov_b32 m0, s62
	v_mfma_f32_16x16x32_bf16 v[80:83], v[240:243], v[194:197], v[80:83]
	v_lshl_add_u64 v[160:161], v[202:203], 0, s[6:7]
	v_mfma_f32_16x16x32_bf16 v[68:71], v[232:235], v[224:227], v[68:71]
	v_mfma_f32_16x16x32_bf16 v[64:67], v[240:243], v[224:227], v[64:67]
	v_mfma_f32_16x16x32_bf16 v[110:113], v[236:239], v[190:193], v[110:113]
	v_mfma_f32_16x16x32_bf16 v[98:101], v[244:247], v[190:193], v[98:101]
	v_mfma_f32_16x16x32_bf16 v[84:87], v[236:239], v[198:201], v[84:87]
	v_mfma_f32_16x16x32_bf16 v[80:83], v[244:247], v[198:201], v[80:83]
	v_mfma_f32_16x16x32_bf16 v[68:71], v[236:239], v[228:231], v[68:71]
	v_mfma_f32_16x16x32_bf16 v[64:67], v[244:247], v[228:231], v[64:67]
	s_barrier
	s_setprio 0
	ds_read_b128 v[186:189], v168 offset:49152
	ds_read_b128 v[190:193], v168 offset:50176
	ds_read_b128 v[194:197], v168 offset:51200
	ds_read_b128 v[198:201], v168 offset:52224
	ds_read_b128 v[224:227], v168 offset:53248
	ds_read_b128 v[228:231], v168 offset:54272
	global_load_lds_dwordx4 v[160:161], off
	v_lshl_add_u64 v[160:161], v[248:249], 0, s[6:7]
	s_mov_b32 m0, s63
	s_mov_b64 exec, s[98:99]
	global_load_lds_dwordx4 v[160:161], off
	s_mov_b64 exec, -1
	s_setprio 1
	s_barrier
	s_waitcnt lgkmcnt(0)
	v_mfma_f32_16x16x32_bf16 v[60:63], v[154:157], v[186:189], v[60:63]
	v_mfma_f32_16x16x32_bf16 v[56:59], v[174:177], v[186:189], v[56:59]
	v_mfma_f32_16x16x32_bf16 v[44:47], v[154:157], v[194:197], v[44:47]
	v_mfma_f32_16x16x32_bf16 v[40:43], v[174:177], v[194:197], v[40:43]
	v_mfma_f32_16x16x32_bf16 v[28:31], v[154:157], v[224:227], v[28:31]
	v_mfma_f32_16x16x32_bf16 v[24:27], v[174:177], v[224:227], v[24:27]
	v_mfma_f32_16x16x32_bf16 v[60:63], v[170:173], v[190:193], v[60:63]
	v_mfma_f32_16x16x32_bf16 v[56:59], v[182:185], v[190:193], v[56:59]
	v_mfma_f32_16x16x32_bf16 v[44:47], v[170:173], v[198:201], v[44:47]
	v_mfma_f32_16x16x32_bf16 v[40:43], v[182:185], v[198:201], v[40:43]
	v_mfma_f32_16x16x32_bf16 v[28:31], v[170:173], v[228:231], v[28:31]
	v_mfma_f32_16x16x32_bf16 v[24:27], v[182:185], v[228:231], v[24:27]
	s_barrier
	s_setprio 0
	s_add_u32 s58, s58, 0x40080
	s_addc_u32 s59, s59, 0
	s_add_i32 s60, s60, s18
	s_mov_b32 m0, s60
	s_nop 0
	global_load_lds_dwordx4 v140, s[58:59]
	s_add_i32 m0, s60, 0x2000
	s_nop 0
	global_load_lds_dwordx4 v144, s[58:59]
	s_waitcnt vmcnt(6)
	s_setprio 1
	s_barrier
	v_mfma_f32_16x16x32_bf16 v[52:55], v[232:235], v[186:189], v[52:55]
	v_mfma_f32_16x16x32_bf16 v[48:51], v[240:243], v[186:189], v[48:51]
	v_mfma_f32_16x16x32_bf16 v[36:39], v[232:235], v[194:197], v[36:39]
	s_add_i32 s71, s71, 2
	v_mfma_f32_16x16x32_bf16 v[32:35], v[240:243], v[194:197], v[32:35]
	s_add_u32 s42, s42, 0x100
	v_mfma_f32_16x16x32_bf16 v[20:23], v[232:235], v[224:227], v[20:23]
	s_addc_u32 s43, s43, 0
	v_mfma_f32_16x16x32_bf16 v[16:19], v[240:243], v[224:227], v[16:19]
	s_add_u32 s69, s69, 0x100
	v_mfma_f32_16x16x32_bf16 v[52:55], v[236:239], v[190:193], v[52:55]
	s_addc_u32 s70, s70, 0
	v_mfma_f32_16x16x32_bf16 v[48:51], v[244:247], v[190:193], v[48:51]
	s_cmp_gt_u32 s71, 13
	v_mfma_f32_16x16x32_bf16 v[36:39], v[236:239], v[198:201], v[36:39]
	v_mfma_f32_16x16x32_bf16 v[32:35], v[244:247], v[198:201], v[32:35]
	v_mfma_f32_16x16x32_bf16 v[20:23], v[236:239], v[228:231], v[20:23]
	v_mfma_f32_16x16x32_bf16 v[16:19], v[244:247], v[228:231], v[16:19]
	s_barrier
	s_setprio 0
	s_cbranch_scc0 .LBB0_465
	s_mul_i32 s42, s67, 0xc0
	s_add_i32 s42, s42, s19
	s_cmpk_lt_u32 s42, 0x2000
	s_cselect_b32 s43, 1, 2
	v_or_b32_e32 v156, s42, v159
	v_mov_b32_e32 v96, s43
	v_cmp_lt_i32_e32 vcc, s23, v156
	v_add_u32_e32 v160, 16, v156
	v_lshl_or_b32 v154, s56, 8, v166
	v_cndmask_b32_e32 v169, 0, v96, vcc
	s_waitcnt vmcnt(0)
	v_add_f32_e32 v96, v126, v127
	v_add_f32_e32 v126, v128, v129
	v_add_f32_e32 v96, v96, v126
	v_mov_b32_e32 v126, v96
	s_nop 1
	v_permlane16_swap_b32_e32 v96, v126
	v_add_f32_e32 v96, v96, v126
	v_mov_b32_e32 v126, v96
	s_nop 1
	v_permlane32_swap_b32_e32 v96, v126
	v_add_f32_e32 v96, v96, v126
	v_fmamk_f32 v96, v96, 0x3a800000, v207
	v_rsq_f32_e32 v162, v96
	v_add_f32_e32 v96, v122, v123
	v_add_f32_e32 v122, v124, v125
	v_add_f32_e32 v96, v96, v122
	v_mov_b32_e32 v122, v96
	s_nop 1
	v_permlane16_swap_b32_e32 v96, v122
	v_add_f32_e32 v96, v96, v122
	v_mov_b32_e32 v122, v96
	s_nop 1
	v_permlane32_swap_b32_e32 v96, v122
	v_add_f32_e32 v96, v96, v122
	v_fmamk_f32 v96, v96, 0x3a800000, v207
	v_rsq_f32_e32 v158, v96
	v_add_f32_e32 v96, v118, v119
	v_add_f32_e32 v118, v120, v121
	v_add_f32_e32 v96, v96, v118
	v_mov_b32_e32 v118, v96
	s_nop 1
	v_permlane16_swap_b32_e32 v96, v118
	v_add_f32_e32 v96, v96, v118
	v_mov_b32_e32 v118, v96
	s_nop 1
	v_permlane32_swap_b32_e32 v96, v118
	v_add_f32_e32 v96, v96, v118
	v_fmamk_f32 v96, v96, 0x3a800000, v207
	v_rsq_f32_e32 v128, v96
	v_add_f32_e32 v96, v114, v115
	v_add_f32_e32 v114, v116, v117
	v_add_f32_e32 v96, v96, v114
	v_mov_b32_e32 v114, v96
	s_nop 1
	v_permlane16_swap_b32_e32 v96, v114
	v_add_f32_e32 v96, v96, v114
	v_mov_b32_e32 v114, v96
	s_nop 1
	v_permlane32_swap_b32_e32 v96, v114
	v_add_f32_e32 v96, v96, v114
	v_fmamk_f32 v96, v96, 0x3a800000, v207
	v_rsq_f32_e32 v126, v96
	v_add_f32_e32 v96, v106, v107
	v_add_f32_e32 v106, v108, v109
	v_add_f32_e32 v96, v96, v106
	v_mov_b32_e32 v106, v96
	s_nop 1
	v_permlane16_swap_b32_e32 v96, v106
	v_add_f32_e32 v96, v96, v106
	v_mov_b32_e32 v106, v96
	s_nop 1
	v_permlane32_swap_b32_e32 v96, v106
	v_add_f32_e32 v96, v96, v106
	v_fmamk_f32 v96, v96, 0x3a800000, v207
	v_rsq_f32_e32 v124, v96
	v_add_f32_e32 v96, v102, v103
	v_add_f32_e32 v102, v104, v105
	v_add_f32_e32 v96, v96, v102
	v_mov_b32_e32 v102, v96
	s_nop 1
	v_permlane16_swap_b32_e32 v96, v102
	v_add_f32_e32 v96, v96, v102
	v_mov_b32_e32 v102, v96
	s_nop 1
	v_permlane32_swap_b32_e32 v96, v102
	v_add_f32_e32 v96, v96, v102
	v_fmamk_f32 v96, v96, 0x3a800000, v207
	v_rsq_f32_e32 v122, v96
	s_mov_b64 s[58:59], -1
	s_cmp_gt_i32 s56, 3
	v_ashrrev_i32_e32 v157, 31, v156
	v_cmp_lt_i32_e32 vcc, s26, v156
	v_cmp_gt_u32_e64 s[42:43], s24, v160
	s_cbranch_scc0 .LBB0_478
	v_lshlrev_b64 v[102:103], 11, v[156:157]
	v_lshl_add_u32 v96, s56, 7, v167
	v_lshl_add_u64 v[102:103], s[48:49], 0, v[102:103]
	v_lshl_add_u64 v[106:107], v[96:97], 1, v[102:103]
	v_pk_fma_f32 v[102:103], v[136:137], v[162:163], v[6:7] op_sel_hi:[1,0,1]
	v_pk_fma_f32 v[104:105], v[134:135], v[162:163], v[4:5] op_sel_hi:[1,0,1]
	v_pk_fma_f32 v[108:109], v[112:113], v[162:163], v[14:15] op_sel_hi:[1,0,1]
	v_pk_fma_f32 v[114:115], v[110:111], v[162:163], v[12:13] op_sel_hi:[1,0,1]
	v_pk_mul_f32 v[108:109], v[102:103], v[108:109]
	v_pk_mul_f32 v[102:103], v[104:105], v[114:115]
	v_pk_fma_f32 v[104:105], v[132:133], v[162:163], v[2:3] op_sel_hi:[1,0,1]
	v_pk_fma_f32 v[114:115], v[130:131], v[162:163], v[0:1] op_sel_hi:[1,0,1]
	v_pk_fma_f32 v[116:117], v[100:101], v[162:163], v[10:11] op_sel_hi:[1,0,1]
	v_pk_fma_f32 v[118:119], v[98:99], v[162:163], v[8:9] op_sel_hi:[1,0,1]
	v_pk_mul_f32 v[116:117], v[104:105], v[116:117]
	v_pk_mul_f32 v[104:105], v[114:115], v[118:119]
	v_cvt_pk_bf16_f32 v102, v102, v103
	v_cvt_pk_bf16_f32 v103, v108, v109
	v_mov_b64_e32 v[120:121], v[14:15]
	v_cvt_pk_bf16_f32 v104, v104, v105
	v_cvt_pk_bf16_f32 v105, v116, v117
	global_store_dwordx4 v[106:107], v[102:105], off
	v_mov_b64_e32 v[116:117], v[10:11]
	v_mov_b64_e32 v[108:109], v[6:7]
	v_cndmask_b32_e64 v102, 2, 1, s[42:43]
	v_cndmask_b32_e32 v125, 0, v102, vcc
	v_mov_b64_e32 v[104:105], v[2:3]
	v_mov_b32_e32 v155, v97
	v_cmp_ne_u32_e32 vcc, v125, v169
	v_mov_b64_e32 v[114:115], v[8:9]
	v_mov_b64_e32 v[102:103], v[0:1]
	v_mov_b64_e32 v[118:119], v[12:13]
	v_mov_b64_e32 v[106:107], v[4:5]
	v_mov_b32_e32 v123, v169
	s_and_saveexec_b64 s[42:43], vcc
	s_cbranch_execz .LBB0_469
	v_mul_u32_u24_e32 v102, 0x7600, v125
	v_lshlrev_b32_e32 v102, 2, v102
	v_mov_b32_e32 v103, v97
	v_lshl_add_u64 v[102:103], s[44:45], 0, v[102:103]
	v_lshl_add_u64 v[118:119], v[154:155], 2, v[102:103]
	global_load_dwordx4 v[102:105], v[118:119], off offset:16
	global_load_dwordx4 v[106:109], v[118:119], off
	global_load_dwordx4 v[114:117], v[118:119], off offset:528
	s_nop 0
	global_load_dwordx4 v[118:121], v[118:119], off offset:512
	v_mov_b32_e32 v123, v125

.LBB0_557:
	s_add_u32 s60, s58, 0xfffc0080
	s_addc_u32 s61, s59, -1
	s_add_i32 s72, 0, 0x10000
	v_add_u32_e32 v96, s72, v193
	ds_read_b128 v[80:83], v96
	ds_read_b128 v[88:91], v96 offset:1024
	ds_read_b128 v[102:105], v96 offset:2048
	ds_read_b128 v[106:109], v96 offset:3072
	s_cmp_eq_u32 s71, 12
	s_cselect_b32 s63, s49, s61
	s_cselect_b32 s62, s67, s60
	s_cselect_b32 s61, s47, s70
	s_cselect_b32 s60, s68, s69
	s_add_i32 m0, s27, 0xc000
	ds_read_b128 v[160:163], v195
	ds_read_b128 v[164:167], v195 offset:1024
	ds_read_b128 v[168:171], v195 offset:2048
	ds_read_b128 v[172:175], v195 offset:3072
	ds_read_b128 v[182:185], v195 offset:4096
	ds_read_b128 v[186:189], v195 offset:5120
	ds_read_b128 v[196:199], v195 offset:6144
	ds_read_b128 v[200:203], v195 offset:7168
	global_load_lds_dwordx4 v156, s[58:59]
	s_add_i32 m0, s27, 0xe000
	s_nop 0
	global_load_lds_dwordx4 v158, s[58:59]
	s_waitcnt lgkmcnt(8)
	s_setprio 1
	s_barrier
	s_waitcnt lgkmcnt(0)
	v_mfma_f32_16x16x32_bf16 v[142:145], v[80:83], v[160:163], v[142:145]
	v_mfma_f32_16x16x32_bf16 v[138:141], v[102:105], v[160:163], v[138:141]
	v_mfma_f32_16x16x32_bf16 v[126:129], v[80:83], v[168:171], v[126:129]
	v_mfma_f32_16x16x32_bf16 v[122:125], v[102:105], v[168:171], v[122:125]
	v_mfma_f32_16x16x32_bf16 v[110:113], v[80:83], v[182:185], v[110:113]
	v_mfma_f32_16x16x32_bf16 v[98:101], v[102:105], v[182:185], v[98:101]
	v_mfma_f32_16x16x32_bf16 v[76:79], v[80:83], v[196:199], v[76:79]
	v_mfma_f32_16x16x32_bf16 v[72:75], v[102:105], v[196:199], v[72:75]
	v_mfma_f32_16x16x32_bf16 v[142:145], v[88:91], v[164:167], v[142:145]
	v_mfma_f32_16x16x32_bf16 v[138:141], v[106:109], v[164:167], v[138:141]
	v_mfma_f32_16x16x32_bf16 v[126:129], v[88:91], v[172:175], v[126:129]
	v_mfma_f32_16x16x32_bf16 v[122:125], v[106:109], v[172:175], v[122:125]
	v_mfma_f32_16x16x32_bf16 v[110:113], v[88:91], v[186:189], v[110:113]
	v_mfma_f32_16x16x32_bf16 v[98:101], v[106:109], v[186:189], v[98:101]
	v_mfma_f32_16x16x32_bf16 v[76:79], v[88:91], v[200:203], v[76:79]
	v_mfma_f32_16x16x32_bf16 v[72:75], v[106:109], v[200:203], v[72:75]
	s_barrier
	s_setprio 0
	s_add_i32 s76, 0, 0x14000
	s_add_i32 s72, s72, s18
	v_add_u32_e32 v96, s76, v193
	v_lshl_add_u64 v[176:177], s[60:61], 0, v[150:151]
	s_mov_b32 m0, s72
	ds_read_b128 v[224:227], v96
	ds_read_b128 v[228:231], v96 offset:1024
	ds_read_b128 v[232:235], v96 offset:2048
	ds_read_b128 v[236:239], v96 offset:3072
	global_load_lds_dwordx4 v150, s[60:61]
	v_lshl_add_u64 v[190:191], s[60:61], 0, v[146:147]
	s_add_i32 m0, s72, 0x2000
	s_nop 0
	global_load_lds_dwordx4 v146, s[60:61]
	s_setprio 1
	s_barrier
	s_waitcnt lgkmcnt(0)
	v_mfma_f32_16x16x32_bf16 v[134:137], v[224:227], v[160:163], v[134:137]
	v_mfma_f32_16x16x32_bf16 v[130:133], v[232:235], v[160:163], v[130:133]
	v_mfma_f32_16x16x32_bf16 v[118:121], v[224:227], v[168:171], v[118:121]
	s_mov_b32 m0, s27
	v_mfma_f32_16x16x32_bf16 v[114:117], v[232:235], v[168:171], v[114:117]
	v_lshl_add_u64 v[240:241], s[62:63], 0, v[152:153]
	v_mfma_f32_16x16x32_bf16 v[92:95], v[224:227], v[182:185], v[92:95]
	v_mfma_f32_16x16x32_bf16 v[84:87], v[232:235], v[182:185], v[84:87]
	v_mfma_f32_16x16x32_bf16 v[68:71], v[224:227], v[196:199], v[68:71]
	v_mfma_f32_16x16x32_bf16 v[64:67], v[232:235], v[196:199], v[64:67]
	v_mfma_f32_16x16x32_bf16 v[134:137], v[228:231], v[164:167], v[134:137]
	v_mfma_f32_16x16x32_bf16 v[130:133], v[236:239], v[164:167], v[130:133]
	v_mfma_f32_16x16x32_bf16 v[118:121], v[228:231], v[172:175], v[118:121]
	v_mfma_f32_16x16x32_bf16 v[114:117], v[236:239], v[172:175], v[114:117]
	v_mfma_f32_16x16x32_bf16 v[92:95], v[228:231], v[186:189], v[92:95]
	v_mfma_f32_16x16x32_bf16 v[84:87], v[236:239], v[186:189], v[84:87]
	v_mfma_f32_16x16x32_bf16 v[68:71], v[228:231], v[200:203], v[68:71]
	v_mfma_f32_16x16x32_bf16 v[64:67], v[236:239], v[200:203], v[64:67]
	s_barrier
	s_setprio 0
	ds_read_b128 v[160:163], v195 offset:16384
	ds_read_b128 v[164:167], v195 offset:17408
	ds_read_b128 v[168:171], v195 offset:18432
	ds_read_b128 v[172:175], v195 offset:19456
	ds_read_b128 v[182:185], v195 offset:20480
	ds_read_b128 v[186:189], v195 offset:21504
	ds_read_b128 v[196:199], v195 offset:22528
	ds_read_b128 v[200:203], v195 offset:23552
	global_load_lds_dwordx4 v152, s[62:63]
	v_lshl_add_u64 v[242:243], s[62:63], 0, v[148:149]
	s_mov_b32 m0, s28
	s_nop 0
	global_load_lds_dwordx4 v148, s[62:63]
	s_setprio 1
	s_barrier
	s_waitcnt lgkmcnt(0)
	v_mfma_f32_16x16x32_bf16 v[60:63], v[80:83], v[160:163], v[60:63]
	v_mfma_f32_16x16x32_bf16 v[56:59], v[102:105], v[160:163], v[56:59]
	v_mfma_f32_16x16x32_bf16 v[44:47], v[80:83], v[168:171], v[44:47]
	v_mfma_f32_16x16x32_bf16 v[40:43], v[102:105], v[168:171], v[40:43]
	v_mfma_f32_16x16x32_bf16 v[28:31], v[80:83], v[182:185], v[28:31]
	v_mfma_f32_16x16x32_bf16 v[24:27], v[102:105], v[182:185], v[24:27]
	v_mfma_f32_16x16x32_bf16 v[12:15], v[80:83], v[196:199], v[12:15]
	v_mfma_f32_16x16x32_bf16 v[8:11], v[102:105], v[196:199], v[8:11]
	v_mfma_f32_16x16x32_bf16 v[60:63], v[88:91], v[164:167], v[60:63]
	v_mfma_f32_16x16x32_bf16 v[56:59], v[106:109], v[164:167], v[56:59]
	v_mfma_f32_16x16x32_bf16 v[44:47], v[88:91], v[172:175], v[44:47]
	v_mfma_f32_16x16x32_bf16 v[40:43], v[106:109], v[172:175], v[40:43]
	v_mfma_f32_16x16x32_bf16 v[28:31], v[88:91], v[186:189], v[28:31]
	v_mfma_f32_16x16x32_bf16 v[24:27], v[106:109], v[186:189], v[24:27]
	v_mfma_f32_16x16x32_bf16 v[12:15], v[88:91], v[200:203], v[12:15]
	v_mfma_f32_16x16x32_bf16 v[8:11], v[106:109], v[200:203], v[8:11]
	s_barrier
	s_setprio 0
	s_add_u32 s74, s60, 0x40000
	s_addc_u32 s75, s61, 0
	s_add_i32 s72, s76, s18
	s_mov_b32 m0, s72
	s_nop 0
	global_load_lds_dwordx4 v150, s[74:75]
	s_add_i32 m0, s72, 0x2000
	s_nop 0
	global_load_lds_dwordx4 v146, s[74:75]
	s_waitcnt vmcnt(6)
	s_setprio 1
	s_barrier
	v_mfma_f32_16x16x32_bf16 v[52:55], v[224:227], v[160:163], v[52:55]
	v_mfma_f32_16x16x32_bf16 v[48:51], v[232:235], v[160:163], v[48:51]
	v_mfma_f32_16x16x32_bf16 v[36:39], v[224:227], v[168:171], v[36:39]
	s_add_i32 s72, 0, 0x18000
	v_mfma_f32_16x16x32_bf16 v[32:35], v[232:235], v[168:171], v[32:35]
	v_add_u32_e32 v96, s72, v193
	v_mfma_f32_16x16x32_bf16 v[20:23], v[224:227], v[182:185], v[20:23]
	v_mfma_f32_16x16x32_bf16 v[16:19], v[232:235], v[182:185], v[16:19]
	v_mfma_f32_16x16x32_bf16 v[4:7], v[224:227], v[196:199], v[4:7]
	v_mfma_f32_16x16x32_bf16 v[0:3], v[232:235], v[196:199], v[0:3]
	v_mfma_f32_16x16x32_bf16 v[52:55], v[228:231], v[164:167], v[52:55]
	v_mfma_f32_16x16x32_bf16 v[48:51], v[236:239], v[164:167], v[48:51]
	v_mfma_f32_16x16x32_bf16 v[36:39], v[228:231], v[172:175], v[36:39]
	v_mfma_f32_16x16x32_bf16 v[32:35], v[236:239], v[172:175], v[32:35]
	v_mfma_f32_16x16x32_bf16 v[20:23], v[228:231], v[186:189], v[20:23]
	v_mfma_f32_16x16x32_bf16 v[16:19], v[236:239], v[186:189], v[16:19]
	v_mfma_f32_16x16x32_bf16 v[4:7], v[228:231], v[200:203], v[4:7]
	v_mfma_f32_16x16x32_bf16 v[0:3], v[236:239], v[200:203], v[0:3]
	s_barrier
	s_setprio 0
	ds_read_b128 v[80:83], v96
	ds_read_b128 v[88:91], v96 offset:1024
	ds_read_b128 v[102:105], v96 offset:2048
	ds_read_b128 v[106:109], v96 offset:3072
	s_add_u32 s62, s62, 0x40000
	s_addc_u32 s63, s63, 0
	s_mov_b32 m0, s37
	ds_read_b128 v[160:163], v195 offset:32768
	ds_read_b128 v[164:167], v195 offset:33792
	ds_read_b128 v[168:171], v195 offset:34816
	ds_read_b128 v[172:175], v195 offset:35840
	ds_read_b128 v[182:185], v195 offset:36864
	ds_read_b128 v[186:189], v195 offset:37888
	ds_read_b128 v[196:199], v195 offset:38912
	ds_read_b128 v[200:203], v195 offset:39936
	global_load_lds_dwordx4 v152, s[62:63]
	s_mov_b32 m0, s56
	s_nop 0
	global_load_lds_dwordx4 v148, s[62:63]
	s_waitcnt lgkmcnt(8)
	s_setprio 1
	s_barrier
	s_waitcnt lgkmcnt(0)
	v_mfma_f32_16x16x32_bf16 v[142:145], v[80:83], v[160:163], v[142:145]
	v_mfma_f32_16x16x32_bf16 v[138:141], v[102:105], v[160:163], v[138:141]
	v_mfma_f32_16x16x32_bf16 v[126:129], v[80:83], v[168:171], v[126:129]
	v_mfma_f32_16x16x32_bf16 v[122:125], v[102:105], v[168:171], v[122:125]
	v_mfma_f32_16x16x32_bf16 v[110:113], v[80:83], v[182:185], v[110:113]
	v_mfma_f32_16x16x32_bf16 v[98:101], v[102:105], v[182:185], v[98:101]
	v_mfma_f32_16x16x32_bf16 v[76:79], v[80:83], v[196:199], v[76:79]
	v_mfma_f32_16x16x32_bf16 v[72:75], v[102:105], v[196:199], v[72:75]
	v_mfma_f32_16x16x32_bf16 v[142:145], v[88:91], v[164:167], v[142:145]
	v_mfma_f32_16x16x32_bf16 v[138:141], v[106:109], v[164:167], v[138:141]
	v_mfma_f32_16x16x32_bf16 v[126:129], v[88:91], v[172:175], v[126:129]
	v_mfma_f32_16x16x32_bf16 v[122:125], v[106:109], v[172:175], v[122:125]
	v_mfma_f32_16x16x32_bf16 v[110:113], v[88:91], v[186:189], v[110:113]
	v_mfma_f32_16x16x32_bf16 v[98:101], v[106:109], v[186:189], v[98:101]
	v_mfma_f32_16x16x32_bf16 v[76:79], v[88:91], v[200:203], v[76:79]
	v_mfma_f32_16x16x32_bf16 v[72:75], v[106:109], v[200:203], v[72:75]
	s_barrier
	s_setprio 0
	s_add_i32 s62, 0, 0x1c000
	s_add_i32 s63, s72, s18
	v_add_u32_e32 v96, s62, v193
	v_lshl_add_u64 v[176:177], v[176:177], 0, s[6:7]
	s_mov_b32 m0, s63
	ds_read_b128 v[224:227], v96
	ds_read_b128 v[228:231], v96 offset:1024
	ds_read_b128 v[232:235], v96 offset:2048
	ds_read_b128 v[236:239], v96 offset:3072
	global_load_lds_dwordx4 v[176:177], off
	v_lshl_add_u64 v[176:177], v[190:191], 0, s[6:7]
	s_add_i32 m0, s63, 0x2000
	s_nop 0
	global_load_lds_dwordx4 v[176:177], off
	s_setprio 1
	s_barrier
	s_waitcnt lgkmcnt(0)
	v_mfma_f32_16x16x32_bf16 v[134:137], v[224:227], v[160:163], v[134:137]
	v_mfma_f32_16x16x32_bf16 v[130:133], v[232:235], v[160:163], v[130:133]
	v_mfma_f32_16x16x32_bf16 v[118:121], v[224:227], v[168:171], v[118:121]
	s_mov_b32 m0, s64
	v_mfma_f32_16x16x32_bf16 v[114:117], v[232:235], v[168:171], v[114:117]
	v_lshl_add_u64 v[176:177], v[240:241], 0, s[6:7]
	v_mfma_f32_16x16x32_bf16 v[92:95], v[224:227], v[182:185], v[92:95]
	v_mfma_f32_16x16x32_bf16 v[84:87], v[232:235], v[182:185], v[84:87]
	v_mfma_f32_16x16x32_bf16 v[68:71], v[224:227], v[196:199], v[68:71]
	v_mfma_f32_16x16x32_bf16 v[64:67], v[232:235], v[196:199], v[64:67]
	v_mfma_f32_16x16x32_bf16 v[134:137], v[228:231], v[164:167], v[134:137]
	v_mfma_f32_16x16x32_bf16 v[130:133], v[236:239], v[164:167], v[130:133]
	v_mfma_f32_16x16x32_bf16 v[118:121], v[228:231], v[172:175], v[118:121]
	v_mfma_f32_16x16x32_bf16 v[114:117], v[236:239], v[172:175], v[114:117]
	v_mfma_f32_16x16x32_bf16 v[92:95], v[228:231], v[186:189], v[92:95]
	v_mfma_f32_16x16x32_bf16 v[84:87], v[236:239], v[186:189], v[84:87]
	v_mfma_f32_16x16x32_bf16 v[68:71], v[228:231], v[200:203], v[68:71]
	v_mfma_f32_16x16x32_bf16 v[64:67], v[236:239], v[200:203], v[64:67]
	s_barrier
	s_setprio 0
	ds_read_b128 v[160:163], v195 offset:49152
	ds_read_b128 v[164:167], v195 offset:50176
	ds_read_b128 v[168:171], v195 offset:51200
	ds_read_b128 v[172:175], v195 offset:52224
	ds_read_b128 v[182:185], v195 offset:53248
	ds_read_b128 v[186:189], v195 offset:54272
	ds_read_b128 v[196:199], v195 offset:55296
	ds_read_b128 v[200:203], v195 offset:56320
	global_load_lds_dwordx4 v[176:177], off
	v_lshl_add_u64 v[176:177], v[242:243], 0, s[6:7]
	s_mov_b32 m0, s65
	s_nop 0
	global_load_lds_dwordx4 v[176:177], off
	s_setprio 1
	s_barrier
	s_waitcnt lgkmcnt(0)
	v_mfma_f32_16x16x32_bf16 v[60:63], v[80:83], v[160:163], v[60:63]
	v_mfma_f32_16x16x32_bf16 v[56:59], v[102:105], v[160:163], v[56:59]
	v_mfma_f32_16x16x32_bf16 v[44:47], v[80:83], v[168:171], v[44:47]
	v_mfma_f32_16x16x32_bf16 v[40:43], v[102:105], v[168:171], v[40:43]
	v_mfma_f32_16x16x32_bf16 v[28:31], v[80:83], v[182:185], v[28:31]
	v_mfma_f32_16x16x32_bf16 v[24:27], v[102:105], v[182:185], v[24:27]
	v_mfma_f32_16x16x32_bf16 v[12:15], v[80:83], v[196:199], v[12:15]
	v_mfma_f32_16x16x32_bf16 v[8:11], v[102:105], v[196:199], v[8:11]
	v_mfma_f32_16x16x32_bf16 v[60:63], v[88:91], v[164:167], v[60:63]
	v_mfma_f32_16x16x32_bf16 v[56:59], v[106:109], v[164:167], v[56:59]
	v_mfma_f32_16x16x32_bf16 v[44:47], v[88:91], v[172:175], v[44:47]
	v_mfma_f32_16x16x32_bf16 v[40:43], v[106:109], v[172:175], v[40:43]
	v_mfma_f32_16x16x32_bf16 v[28:31], v[88:91], v[186:189], v[28:31]
	v_mfma_f32_16x16x32_bf16 v[24:27], v[106:109], v[186:189], v[24:27]
	v_mfma_f32_16x16x32_bf16 v[12:15], v[88:91], v[200:203], v[12:15]
	v_mfma_f32_16x16x32_bf16 v[8:11], v[106:109], v[200:203], v[8:11]
	s_barrier
	s_setprio 0
	s_add_u32 s60, s60, 0x40080
	s_addc_u32 s61, s61, 0
	s_add_i32 s62, s62, s18
	s_mov_b32 m0, s62
	s_nop 0
	global_load_lds_dwordx4 v150, s[60:61]
	s_add_i32 m0, s62, 0x2000
	s_nop 0
	global_load_lds_dwordx4 v146, s[60:61]
	s_waitcnt vmcnt(6)
	s_setprio 1
	s_barrier
	v_mfma_f32_16x16x32_bf16 v[52:55], v[224:227], v[160:163], v[52:55]
	v_mfma_f32_16x16x32_bf16 v[48:51], v[232:235], v[160:163], v[48:51]
	v_mfma_f32_16x16x32_bf16 v[36:39], v[224:227], v[168:171], v[36:39]
	s_add_i32 s71, s71, 2
	v_mfma_f32_16x16x32_bf16 v[32:35], v[232:235], v[168:171], v[32:35]
	s_add_u32 s58, s58, 0x100
	v_mfma_f32_16x16x32_bf16 v[20:23], v[224:227], v[182:185], v[20:23]
	s_addc_u32 s59, s59, 0
	v_mfma_f32_16x16x32_bf16 v[16:19], v[232:235], v[182:185], v[16:19]
	s_add_u32 s69, s69, 0x100
	v_mfma_f32_16x16x32_bf16 v[4:7], v[224:227], v[196:199], v[4:7]
	s_addc_u32 s70, s70, 0
	v_mfma_f32_16x16x32_bf16 v[0:3], v[232:235], v[196:199], v[0:3]
	s_cmp_gt_u32 s71, 13
	v_mfma_f32_16x16x32_bf16 v[52:55], v[228:231], v[164:167], v[52:55]
	v_mfma_f32_16x16x32_bf16 v[48:51], v[236:239], v[164:167], v[48:51]
	v_mfma_f32_16x16x32_bf16 v[36:39], v[228:231], v[172:175], v[36:39]
	v_mfma_f32_16x16x32_bf16 v[32:35], v[236:239], v[172:175], v[32:35]
	v_mfma_f32_16x16x32_bf16 v[20:23], v[228:231], v[186:189], v[20:23]
	v_mfma_f32_16x16x32_bf16 v[16:19], v[236:239], v[186:189], v[16:19]
	v_mfma_f32_16x16x32_bf16 v[4:7], v[228:231], v[200:203], v[4:7]
	v_mfma_f32_16x16x32_bf16 v[0:3], v[236:239], v[200:203], v[0:3]
	s_barrier
	s_setprio 0
	s_cbranch_scc0 .LBB0_557
	s_lshl_b32 s47, s54, 8
	s_add_i32 s47, s47, s57
	v_or_b32_e32 v162, s47, v192
	v_ashrrev_i32_e32 v163, 31, v162
	v_or_b32_e32 v190, 16, v162
	v_lshlrev_b64 v[80:81], 6, v[162:163]
	v_ashrrev_i32_e32 v191, 31, v190
	v_or_b32_e32 v188, 32, v162
	v_lshl_add_u64 v[80:81], v[154:155], 0, v[80:81]
	v_lshlrev_b64 v[82:83], 6, v[190:191]
	v_ashrrev_i32_e32 v189, 31, v188
	v_lshl_add_u64 v[82:83], v[154:155], 0, v[82:83]
	global_load_dwordx4 v[174:177], v[80:81], off
	global_load_dwordx4 v[196:199], v[82:83], off
	v_lshlrev_b64 v[80:81], 6, v[188:189]
	v_or_b32_e32 v186, 48, v162
	v_lshl_add_u64 v[80:81], v[154:155], 0, v[80:81]
	v_ashrrev_i32_e32 v187, 31, v186
	global_load_dwordx4 v[200:203], v[80:81], off
	v_lshlrev_b64 v[80:81], 6, v[186:187]
	v_lshl_add_u64 v[80:81], v[154:155], 0, v[80:81]
	v_add_u32_e32 v184, 0x80, v162
	global_load_dwordx4 v[224:227], v[80:81], off
	v_ashrrev_i32_e32 v185, 31, v184
	v_lshlrev_b64 v[80:81], 6, v[184:185]
	v_lshl_add_u64 v[80:81], v[154:155], 0, v[80:81]
	global_load_dwordx4 v[228:231], v[80:81], off
	v_add_u32_e32 v172, 0x90, v162
	v_ashrrev_i32_e32 v173, 31, v172
	v_lshlrev_b64 v[80:81], 6, v[172:173]
	v_lshl_add_u64 v[80:81], v[154:155], 0, v[80:81]
	global_load_dwordx4 v[232:235], v[80:81], off
	v_add_u32_e32 v168, 0xa0, v162
	v_ashrrev_i32_e32 v169, 31, v168
	v_lshlrev_b64 v[80:81], 6, v[168:169]
	v_lshl_add_u64 v[80:81], v[154:155], 0, v[80:81]
	global_load_dwordx4 v[236:239], v[80:81], off
	v_add_u32_e32 v164, 0xb0, v162
	v_ashrrev_i32_e32 v165, 31, v164
	v_lshlrev_b64 v[80:81], 6, v[164:165]
	s_cmpk_lt_u32 s47, 0x2000
	v_lshl_add_u64 v[80:81], v[154:155], 0, v[80:81]
	s_cselect_b32 s47, 1, 2
	global_load_dwordx4 v[240:243], v[80:81], off
	v_mov_b32_e32 v218, s47
	v_cmp_lt_i32_e32 vcc, s23, v162
	v_lshl_or_b32 v166, s55, 8, v194
	v_ashrrev_i32_e32 v167, 31, v166
	v_cndmask_b32_e32 v185, 0, v218, vcc
	v_mul_u32_u24_e32 v82, 0x7600, v185
	v_lshlrev_b32_e32 v96, 2, v82
	v_lshl_add_u64 v[80:81], s[44:45], 0, v[96:97]
	v_lshl_add_u64 v[106:107], v[166:167], 2, v[80:81]
	global_load_dwordx4 v[80:83], v[106:107], off offset:16
	global_load_dwordx4 v[88:91], v[106:107], off
	global_load_dwordx4 v[102:105], v[106:107], off offset:528
	s_nop 0
	global_load_dwordx4 v[106:109], v[106:107], off offset:512
	v_lshl_or_b32 v160, s55, 7, v194
	v_cmp_lt_i32_e32 vcc, s23, v190
	s_waitcnt vmcnt(0)
	v_add_f32_e32 v96, v174, v175
	v_add_f32_e32 v161, v176, v177
	v_add_f32_e32 v96, v96, v161
	v_add_f32_e32 v161, v196, v197
	v_add_f32_e32 v163, v198, v199
	v_add_f32_e32 v161, v161, v163
	v_add_f32_e32 v165, v200, v201
	v_add_f32_e32 v169, v202, v203
	v_add_f32_e32 v163, v165, v169
	v_mov_b32_e32 v169, v161
	v_add_f32_e32 v170, v224, v225
	v_add_f32_e32 v171, v226, v227
	v_add_f32_e32 v165, v170, v171
	v_mov_b32_e32 v170, v163
	v_permlane16_swap_b32_e32 v161, v169
	s_nop 0
	v_permlane16_swap_b32_e32 v163, v170
	v_add_f32_e32 v201, v161, v169
	v_add_f32_e32 v199, v163, v170
	v_add_f32_e32 v161, v228, v229
	v_add_f32_e32 v163, v230, v231
	v_add_f32_e32 v161, v161, v163
	v_mov_b32_e32 v163, v161
	s_nop 1
	v_permlane16_swap_b32_e32 v161, v163
	v_add_f32_e32 v191, v161, v163
	v_add_f32_e32 v161, v232, v233
	v_add_f32_e32 v163, v234, v235
	v_add_f32_e32 v161, v161, v163
	v_mov_b32_e32 v173, v96
	v_mov_b32_e32 v163, v161
	s_nop 0
	v_permlane16_swap_b32_e32 v96, v173
	v_permlane16_swap_b32_e32 v161, v163
	v_add_f32_e32 v96, v96, v173
	v_add_f32_e32 v187, v161, v163
	v_add_f32_e32 v161, v236, v237
	v_add_f32_e32 v163, v238, v239
	v_mov_b32_e32 v173, v96
	v_add_f32_e32 v161, v161, v163
	s_nop 0
	v_permlane32_swap_b32_e32 v96, v173
	v_mov_b32_e32 v163, v161
	v_add_f32_e32 v96, v96, v173
	s_nop 0
	v_permlane16_swap_b32_e32 v161, v163
	v_fmamk_f32 v96, v96, 0x3a800000, v207
	v_add_f32_e32 v169, v161, v163
	v_add_f32_e32 v161, v240, v241
	v_add_f32_e32 v163, v242, v243
	v_mov_b32_e32 v171, v165
	v_rsq_f32_e32 v96, v96
	v_add_f32_e32 v161, v161, v163
	v_permlane16_swap_b32_e32 v165, v171
	v_mov_b32_e32 v163, v161
	v_add_f32_e32 v197, v165, v171
	s_nop 0
	v_permlane16_swap_b32_e32 v161, v163
	v_mov_b64_e32 v[170:171], s[42:43]
	v_add_f32_e32 v163, v161, v163
	v_ashrrev_i32_e32 v161, 31, v160
	v_mad_i64_i32 v[170:171], s[54:55], v162, s31, v[170:171]
	v_lshl_add_u64 v[224:225], v[160:161], 1, v[170:171]
	v_pk_mul_f32 v[182:183], v[82:83], s[0:1] op_sel_hi:[1,0]
	v_pk_mul_f32 v[176:177], v[80:81], s[0:1] op_sel_hi:[1,0]
	v_pk_mul_f32 v[174:175], v[90:91], s[0:1] op_sel_hi:[1,0]
	v_pk_mul_f32 v[170:171], v[88:89], s[0:1] op_sel_hi:[1,0]
	v_mul_f32_e32 v226, 0xbfb8aa3b, v96
	v_pk_fma_f32 v[228:229], v[144:145], v[226:227], v[174:175] op_sel_hi:[1,0,1]
	v_pk_fma_f32 v[230:231], v[142:143], v[226:227], v[170:171] op_sel_hi:[1,0,1]
	v_pk_fma_f32 v[232:233], v[140:141], v[226:227], v[182:183] op_sel_hi:[1,0,1]
	v_pk_fma_f32 v[226:227], v[138:139], v[226:227], v[176:177] op_sel_hi:[1,0,1]
	v_exp_f32_e32 v230, v230
	v_exp_f32_e32 v226, v226
	v_exp_f32_e32 v231, v231
	v_exp_f32_e32 v227, v227
	v_exp_f32_e32 v232, v232
	v_exp_f32_e32 v233, v233
	v_exp_f32_e32 v228, v228
	v_exp_f32_e32 v229, v229
	v_pk_add_f32 v[230:231], v[230:231], 1.0 op_sel_hi:[1,0]
	v_pk_add_f32 v[232:233], v[232:233], 1.0 op_sel_hi:[1,0]
	v_pk_add_f32 v[226:227], v[226:227], 1.0 op_sel_hi:[1,0]
	v_pk_add_f32 v[228:229], v[228:229], 1.0 op_sel_hi:[1,0]
	v_rcp_f32_e32 v230, v230
	v_rcp_f32_e32 v226, v226
	v_rcp_f32_e32 v231, v231
	v_rcp_f32_e32 v227, v227
	v_rcp_f32_e32 v232, v232
	v_rcp_f32_e32 v233, v233
	v_rcp_f32_e32 v228, v228
	v_rcp_f32_e32 v229, v229
	v_pk_fma_f32 v[142:143], v[142:143], v[96:97], v[88:89] op_sel_hi:[1,0,1]
	v_pk_fma_f32 v[140:141], v[140:141], v[96:97], v[82:83] op_sel_hi:[1,0,1]
	v_pk_fma_f32 v[138:139], v[138:139], v[96:97], v[80:81] op_sel_hi:[1,0,1]
	v_pk_fma_f32 v[134:135], v[134:135], v[96:97], v[106:107] op_sel_hi:[1,0,1]
	v_pk_fma_f32 v[132:133], v[132:133], v[96:97], v[104:105] op_sel_hi:[1,0,1]
	v_pk_fma_f32 v[130:131], v[130:131], v[96:97], v[102:103] op_sel_hi:[1,0,1]
	v_pk_fma_f32 v[144:145], v[144:145], v[96:97], v[90:91] op_sel_hi:[1,0,1]
	v_pk_fma_f32 v[136:137], v[136:137], v[96:97], v[108:109] op_sel_hi:[1,0,1]
	v_pk_mul_f32 v[134:135], v[142:143], v[134:135]
	v_pk_mul_f32 v[132:133], v[140:141], v[132:133]
	v_pk_mul_f32 v[130:131], v[138:139], v[130:131]
	v_pk_mul_f32 v[136:137], v[144:145], v[136:137]
	v_pk_mul_f32 v[134:135], v[134:135], v[230:231]
	v_pk_mul_f32 v[138:139], v[132:133], v[232:233]
	v_pk_mul_f32 v[132:133], v[130:131], v[226:227]
	v_cvt_pk_bf16_f32 v130, v134, v135
	v_mov_b32_e32 v202, v201
	v_mov_b32_e32 v200, v199
	v_mov_b32_e32 v198, v197
	v_mov_b32_e32 v196, v191
	v_mov_b32_e32 v189, v187
	v_mov_b32_e32 v173, v169
	v_mov_b32_e32 v165, v163
	v_pk_mul_f32 v[136:137], v[136:137], v[228:229]
	v_permlane32_swap_b32_e32 v201, v202
	v_cvt_pk_bf16_f32 v131, v136, v137
	v_cvt_pk_bf16_f32 v132, v132, v133
	v_cvt_pk_bf16_f32 v133, v138, v139
	global_store_dwordx4 v[224:225], v[130:133], off
	v_permlane32_swap_b32_e32 v199, v200
	s_nop 0
	v_cndmask_b32_e32 v130, 0, v218, vcc
	v_permlane32_swap_b32_e32 v197, v198
	v_permlane32_swap_b32_e32 v191, v196
	v_permlane32_swap_b32_e32 v187, v189
	v_permlane32_swap_b32_e32 v169, v173
	v_permlane32_swap_b32_e32 v163, v165
	v_cmp_ne_u32_e32 vcc, v130, v185
	s_and_saveexec_b64 s[54:55], vcc
	s_cbranch_execz .LBB0_560
	v_mul_u32_u24_e32 v80, 0x7600, v130
	v_lshlrev_b32_e32 v96, 2, v80
	v_lshl_add_u64 v[80:81], s[44:45], 0, v[96:97]
	v_lshl_add_u64 v[106:107], v[166:167], 2, v[80:81]
	global_load_dwordx4 v[88:91], v[106:107], off
	global_load_dwordx4 v[80:83], v[106:107], off offset:16
	global_load_dwordx4 v[102:105], v[106:107], off offset:528
	s_nop 0
	global_load_dwordx4 v[106:109], v[106:107], off offset:512
	v_mov_b32_e32 v185, v130
	s_waitcnt vmcnt(0)
	v_pk_mul_f32 v[170:171], v[88:89], s[0:1] op_sel_hi:[1,0]
	v_pk_mul_f32 v[174:175], v[90:91], s[0:1] op_sel_hi:[1,0]
	v_pk_mul_f32 v[176:177], v[80:81], s[0:1] op_sel_hi:[1,0]
	v_pk_mul_f32 v[182:183], v[82:83], s[0:1] op_sel_hi:[1,0]

.LBB0_1021:
	s_add_i32 vcc_hi, s46, 2
	s_add_u32 s84, s44, 0x80
	s_addc_u32 s47, s45, 0
	s_add_i32 s29, 0, 0x10000
	v_add_u32_e32 v96, s29, v225
	ds_read_b128 v[56:59], v96
	ds_read_b128 v[68:71], v96 offset:1024
	ds_read_b128 v[80:83], v96 offset:2048
	ds_read_b128 v[98:101], v96 offset:3072
	s_cmp_eq_u32 s90, s46
	s_cselect_b32 s46, s80, s84
	s_cselect_b32 s47, s81, s47
	s_cselect_b32 s85, s83, vcc_lo
	s_cselect_b32 s84, s82, s87
	s_add_i32 m0, s2, 0xc000
	ds_read_b128 v[102:105], v227
	ds_read_b128 v[112:115], v227 offset:1024
	ds_read_b128 v[124:127], v227 offset:2048
	ds_read_b128 v[192:195], v227 offset:3072
	ds_read_b128 v[196:199], v227 offset:4096
	ds_read_b128 v[200:203], v227 offset:5120
	global_load_lds_dwordx4 v188, s[44:45]
	s_add_i32 m0, s2, 0xe000
	s_mov_b64 exec, s[98:99]
	global_load_lds_dwordx4 v190, s[44:45]
	s_mov_b64 exec, -1
	s_waitcnt lgkmcnt(8)
	s_setprio 1
	s_barrier
	s_waitcnt lgkmcnt(0)
	v_mfma_f32_16x16x32_bf16 v[172:175], v[56:59], v[102:105], v[172:175]
	v_mfma_f32_16x16x32_bf16 v[168:171], v[80:83], v[102:105], v[168:171]
	v_mfma_f32_16x16x32_bf16 v[156:159], v[56:59], v[124:127], v[156:159]
	v_mfma_f32_16x16x32_bf16 v[152:155], v[80:83], v[124:127], v[152:155]
	v_mfma_f32_16x16x32_bf16 v[132:135], v[56:59], v[196:199], v[132:135]
	v_mfma_f32_16x16x32_bf16 v[128:131], v[80:83], v[196:199], v[128:131]
	v_mfma_f32_16x16x32_bf16 v[172:175], v[68:71], v[112:115], v[172:175]
	v_mfma_f32_16x16x32_bf16 v[168:171], v[98:101], v[112:115], v[168:171]
	v_mfma_f32_16x16x32_bf16 v[156:159], v[68:71], v[192:195], v[156:159]
	v_mfma_f32_16x16x32_bf16 v[152:155], v[98:101], v[192:195], v[152:155]
	v_mfma_f32_16x16x32_bf16 v[132:135], v[68:71], v[200:203], v[132:135]
	v_mfma_f32_16x16x32_bf16 v[128:131], v[98:101], v[200:203], v[128:131]
	s_barrier
	s_setprio 0
	s_add_i32 s96, 0, 0x14000
	s_add_i32 s29, s29, s18
	v_add_u32_e32 v96, s96, v225
	v_lshl_add_u64 v[106:107], s[84:85], 0, v[182:183]
	s_mov_b32 m0, s29
	ds_read_b128 v[228:231], v96
	ds_read_b128 v[232:235], v96 offset:1024
	ds_read_b128 v[236:239], v96 offset:2048
	ds_read_b128 v[240:243], v96 offset:3072
	global_load_lds_dwordx4 v182, s[84:85]
	v_lshl_add_u64 v[248:249], s[84:85], 0, v[186:187]
	s_add_i32 m0, s29, 0x2000
	s_nop 0
	global_load_lds_dwordx4 v186, s[84:85]
	s_setprio 1
	s_barrier
	s_waitcnt lgkmcnt(0)
	v_mfma_f32_16x16x32_bf16 v[164:167], v[228:231], v[102:105], v[164:167]
	v_mfma_f32_16x16x32_bf16 v[102:105], v[236:239], v[102:105], v[160:163]
	v_mfma_f32_16x16x32_bf16 v[120:123], v[228:231], v[196:199], v[120:123]
	s_mov_b32 m0, s2
	v_mfma_f32_16x16x32_bf16 v[116:119], v[236:239], v[196:199], v[116:119]
	v_lshl_add_u64 v[250:251], s[46:47], 0, v[176:177]
	v_mfma_f32_16x16x32_bf16 v[164:167], v[232:235], v[112:115], v[164:167]
	v_mfma_f32_16x16x32_bf16 v[102:105], v[240:243], v[112:115], v[102:105]
	v_mfma_f32_16x16x32_bf16 v[112:115], v[228:231], v[124:127], v[148:151]
	v_mfma_f32_16x16x32_bf16 v[124:127], v[236:239], v[124:127], v[144:147]
	v_mfma_f32_16x16x32_bf16 v[120:123], v[232:235], v[200:203], v[120:123]
	v_mfma_f32_16x16x32_bf16 v[116:119], v[240:243], v[200:203], v[116:119]
	v_mfma_f32_16x16x32_bf16 v[112:115], v[232:235], v[192:195], v[112:115]
	v_mfma_f32_16x16x32_bf16 v[124:127], v[240:243], v[192:195], v[124:127]
	s_barrier
	s_setprio 0
	ds_read_b128 v[144:147], v227 offset:16384
	ds_read_b128 v[148:151], v227 offset:17408
	ds_read_b128 v[160:163], v227 offset:18432
	ds_read_b128 v[192:195], v227 offset:19456
	ds_read_b128 v[196:199], v227 offset:20480
	ds_read_b128 v[200:203], v227 offset:21504
	global_load_lds_dwordx4 v176, s[46:47]
	v_lshl_add_u64 v[252:253], s[46:47], 0, v[184:185]
	s_mov_b32 m0, s3
	s_mov_b64 exec, s[98:99]
	global_load_lds_dwordx4 v184, s[46:47]
	s_mov_b64 exec, -1
	s_setprio 1
	s_barrier
	s_waitcnt lgkmcnt(0)
	v_mfma_f32_16x16x32_bf16 v[88:91], v[56:59], v[144:147], v[88:91]
	v_mfma_f32_16x16x32_bf16 v[84:87], v[80:83], v[144:147], v[84:87]
	v_mfma_f32_16x16x32_bf16 v[52:55], v[56:59], v[160:163], v[52:55]
	v_mfma_f32_16x16x32_bf16 v[48:51], v[80:83], v[160:163], v[48:51]
	v_mfma_f32_16x16x32_bf16 v[28:31], v[56:59], v[196:199], v[28:31]
	v_mfma_f32_16x16x32_bf16 v[24:27], v[80:83], v[196:199], v[24:27]
	v_mfma_f32_16x16x32_bf16 v[88:91], v[68:71], v[148:151], v[88:91]
	v_mfma_f32_16x16x32_bf16 v[84:87], v[98:101], v[148:151], v[84:87]
	v_mfma_f32_16x16x32_bf16 v[52:55], v[68:71], v[192:195], v[52:55]
	v_mfma_f32_16x16x32_bf16 v[48:51], v[98:101], v[192:195], v[48:51]
	v_mfma_f32_16x16x32_bf16 v[28:31], v[68:71], v[200:203], v[28:31]
	v_mfma_f32_16x16x32_bf16 v[24:27], v[98:101], v[200:203], v[24:27]
	s_barrier
	s_setprio 0
	s_add_u32 s84, s84, s57
	s_addc_u32 s85, s85, 0
	s_add_i32 s29, s96, s18
	v_lshl_add_u64 v[218:219], s[84:85], 0, v[182:183]
	s_mov_b32 m0, s29
	v_lshl_add_u64 v[220:221], s[84:85], 0, v[186:187]
	global_load_lds_dwordx4 v182, s[84:85]
	s_add_i32 m0, s29, 0x2000
	s_nop 0
	global_load_lds_dwordx4 v186, s[84:85]
	s_waitcnt vmcnt(6)
	s_setprio 1
	s_barrier
	v_mfma_f32_16x16x32_bf16 v[44:47], v[228:231], v[160:163], v[44:47]
	v_mfma_f32_16x16x32_bf16 v[40:43], v[236:239], v[160:163], v[40:43]
	v_mfma_f32_16x16x32_bf16 v[20:23], v[228:231], v[196:199], v[20:23]
	s_add_i32 s29, 0, 0x18000
	v_mfma_f32_16x16x32_bf16 v[16:19], v[236:239], v[196:199], v[16:19]
	v_add_u32_e32 v96, s29, v225
	v_mfma_f32_16x16x32_bf16 v[56:59], v[228:231], v[144:147], v[76:79]
	v_mfma_f32_16x16x32_bf16 v[68:71], v[236:239], v[144:147], v[72:75]
	v_mfma_f32_16x16x32_bf16 v[44:47], v[232:235], v[192:195], v[44:47]
	v_mfma_f32_16x16x32_bf16 v[40:43], v[240:243], v[192:195], v[40:43]
	v_mfma_f32_16x16x32_bf16 v[20:23], v[232:235], v[200:203], v[20:23]
	v_mfma_f32_16x16x32_bf16 v[16:19], v[240:243], v[200:203], v[16:19]
	v_mfma_f32_16x16x32_bf16 v[56:59], v[232:235], v[148:151], v[56:59]
	v_mfma_f32_16x16x32_bf16 v[68:71], v[240:243], v[148:151], v[68:71]
	s_barrier
	s_setprio 0
	ds_read_b128 v[72:75], v96
	ds_read_b128 v[76:79], v96 offset:1024
	ds_read_b128 v[80:83], v96 offset:2048
	ds_read_b128 v[98:101], v96 offset:3072
	s_add_u32 s46, s46, s64
	s_addc_u32 s47, s47, 0
	s_mov_b32 m0, s4
	ds_read_b128 v[144:147], v227 offset:32768
	ds_read_b128 v[148:151], v227 offset:33792
	ds_read_b128 v[192:195], v227 offset:34816
	ds_read_b128 v[196:199], v227 offset:35840
	ds_read_b128 v[200:203], v227 offset:36864
	ds_read_b128 v[228:231], v227 offset:37888
	global_load_lds_dwordx4 v176, s[46:47]
	s_mov_b32 m0, s5
	s_mov_b64 exec, s[98:99]
	global_load_lds_dwordx4 v184, s[46:47]
	s_mov_b64 exec, -1
	s_waitcnt lgkmcnt(8)
	s_setprio 1
	s_barrier
	s_waitcnt lgkmcnt(0)
	v_mfma_f32_16x16x32_bf16 v[160:163], v[72:75], v[144:147], v[172:175]
	v_mfma_f32_16x16x32_bf16 v[172:175], v[76:79], v[148:151], v[160:163]
	v_mfma_f32_16x16x32_bf16 v[160:163], v[80:83], v[144:147], v[168:171]
	v_mfma_f32_16x16x32_bf16 v[156:159], v[72:75], v[192:195], v[156:159]
	v_mfma_f32_16x16x32_bf16 v[152:155], v[80:83], v[192:195], v[152:155]
	v_mfma_f32_16x16x32_bf16 v[132:135], v[72:75], v[200:203], v[132:135]
	v_mfma_f32_16x16x32_bf16 v[128:131], v[80:83], v[200:203], v[128:131]
	v_mfma_f32_16x16x32_bf16 v[168:171], v[98:101], v[148:151], v[160:163]
	v_mfma_f32_16x16x32_bf16 v[156:159], v[76:79], v[196:199], v[156:159]
	v_mfma_f32_16x16x32_bf16 v[152:155], v[98:101], v[196:199], v[152:155]
	v_mfma_f32_16x16x32_bf16 v[132:135], v[76:79], v[228:231], v[132:135]
	v_mfma_f32_16x16x32_bf16 v[128:131], v[98:101], v[228:231], v[128:131]
	s_barrier
	s_setprio 0
	s_add_i32 s46, 0, 0x1c000
	s_add_i32 s29, s29, s18
	v_add_u32_e32 v96, s46, v225
	v_lshl_add_u64 v[106:107], v[106:107], 0, s[6:7]
	s_mov_b32 m0, s29
	ds_read_b128 v[232:235], v96
	ds_read_b128 v[236:239], v96 offset:1024
	ds_read_b128 v[240:243], v96 offset:2048
	ds_read_b128 v[244:247], v96 offset:3072
	global_load_lds_dwordx4 v[106:107], off
	v_lshl_add_u64 v[106:107], v[248:249], 0, s[6:7]
	s_add_i32 m0, s29, 0x2000
	s_nop 0
	global_load_lds_dwordx4 v[106:107], off
	s_setprio 1
	s_barrier
	s_waitcnt lgkmcnt(0)
	v_mfma_f32_16x16x32_bf16 v[160:163], v[232:235], v[144:147], v[164:167]
	v_mfma_f32_16x16x32_bf16 v[102:105], v[240:243], v[144:147], v[102:105]
	v_mfma_f32_16x16x32_bf16 v[164:167], v[236:239], v[148:151], v[160:163]
	s_mov_b32 m0, s88
	v_mfma_f32_16x16x32_bf16 v[160:163], v[244:247], v[148:151], v[102:105]
	v_lshl_add_u64 v[106:107], v[250:251], 0, s[6:7]
	v_mfma_f32_16x16x32_bf16 v[102:105], v[232:235], v[192:195], v[112:115]
	v_mfma_f32_16x16x32_bf16 v[148:151], v[236:239], v[196:199], v[102:105]
	v_mfma_f32_16x16x32_bf16 v[102:105], v[240:243], v[192:195], v[124:127]
	v_mfma_f32_16x16x32_bf16 v[144:147], v[244:247], v[196:199], v[102:105]
	v_mfma_f32_16x16x32_bf16 v[102:105], v[232:235], v[200:203], v[120:123]
	v_mfma_f32_16x16x32_bf16 v[120:123], v[236:239], v[228:231], v[102:105]
	v_mfma_f32_16x16x32_bf16 v[102:105], v[240:243], v[200:203], v[116:119]
	v_mfma_f32_16x16x32_bf16 v[116:119], v[244:247], v[228:231], v[102:105]
	s_barrier
	s_setprio 0
	s_nop 2
	ds_read_b128 v[102:105], v227 offset:49152
	ds_read_b128 v[112:115], v227 offset:50176
	ds_read_b128 v[124:127], v227 offset:51200
	ds_read_b128 v[192:195], v227 offset:52224
	ds_read_b128 v[196:199], v227 offset:53248
	ds_read_b128 v[200:203], v227 offset:54272
	global_load_lds_dwordx4 v[106:107], off
	v_lshl_add_u64 v[106:107], v[252:253], 0, s[6:7]
	s_mov_b32 m0, s89
	s_mov_b64 exec, s[98:99]
	global_load_lds_dwordx4 v[106:107], off
	s_mov_b64 exec, -1
	s_setprio 1
	s_barrier
	s_waitcnt lgkmcnt(0)
	v_mfma_f32_16x16x32_bf16 v[88:91], v[72:75], v[102:105], v[88:91]
	v_mfma_f32_16x16x32_bf16 v[84:87], v[80:83], v[102:105], v[84:87]
	v_mfma_f32_16x16x32_bf16 v[52:55], v[72:75], v[124:127], v[52:55]
	v_mfma_f32_16x16x32_bf16 v[48:51], v[80:83], v[124:127], v[48:51]
	v_mfma_f32_16x16x32_bf16 v[28:31], v[72:75], v[196:199], v[28:31]
	v_mfma_f32_16x16x32_bf16 v[24:27], v[80:83], v[196:199], v[24:27]
	v_mfma_f32_16x16x32_bf16 v[88:91], v[76:79], v[112:115], v[88:91]
	v_mfma_f32_16x16x32_bf16 v[84:87], v[98:101], v[112:115], v[84:87]
	v_mfma_f32_16x16x32_bf16 v[52:55], v[76:79], v[192:195], v[52:55]
	v_mfma_f32_16x16x32_bf16 v[48:51], v[98:101], v[192:195], v[48:51]
	v_mfma_f32_16x16x32_bf16 v[28:31], v[76:79], v[200:203], v[28:31]
	v_mfma_f32_16x16x32_bf16 v[24:27], v[98:101], v[200:203], v[24:27]
	s_barrier
	s_setprio 0
	s_add_i32 s29, s46, s18
	v_lshl_add_u64 v[72:73], v[218:219], 0, s[6:7]
	s_mov_b32 m0, s29
	s_nop 0
	global_load_lds_dwordx4 v[72:73], off
	v_lshl_add_u64 v[72:73], v[220:221], 0, s[6:7]
	s_add_i32 m0, s29, 0x2000
	s_nop 0
	global_load_lds_dwordx4 v[72:73], off
	s_waitcnt vmcnt(6)
	s_setprio 1
	s_barrier
	v_mfma_f32_16x16x32_bf16 v[56:59], v[232:235], v[102:105], v[56:59]
	v_mfma_f32_16x16x32_bf16 v[76:79], v[236:239], v[112:115], v[56:59]
	v_mfma_f32_16x16x32_bf16 v[56:59], v[240:243], v[102:105], v[68:71]
	s_add_u32 s44, s44, 0x100
	v_mfma_f32_16x16x32_bf16 v[44:47], v[232:235], v[124:127], v[44:47]
	s_addc_u32 s45, s45, 0
	v_mfma_f32_16x16x32_bf16 v[40:43], v[240:243], v[124:127], v[40:43]
	s_add_u32 s87, s87, 0x100
	v_mfma_f32_16x16x32_bf16 v[20:23], v[232:235], v[196:199], v[20:23]
	s_addc_u32 vcc_lo, vcc_lo, 0
	v_mfma_f32_16x16x32_bf16 v[16:19], v[240:243], v[196:199], v[16:19]
	s_cmp_ge_u32 vcc_hi, s37
	v_mfma_f32_16x16x32_bf16 v[72:75], v[244:247], v[112:115], v[56:59]
	s_mov_b32 s46, vcc_hi
	v_mfma_f32_16x16x32_bf16 v[44:47], v[236:239], v[192:195], v[44:47]
	v_mfma_f32_16x16x32_bf16 v[40:43], v[244:247], v[192:195], v[40:43]
	v_mfma_f32_16x16x32_bf16 v[20:23], v[236:239], v[200:203], v[20:23]
	v_mfma_f32_16x16x32_bf16 v[16:19], v[244:247], v[200:203], v[16:19]
	s_barrier
	s_setprio 0
	s_cbranch_scc0 .LBB0_1021
	s_mul_i32 s44, s86, 0xc0
	s_add_i32 s44, s44, s19
	s_cmpk_lt_u32 s44, 0x2000
	v_or_b32_e32 v198, s44, v223
	s_cselect_b32 s44, 1, 2
	v_mov_b32_e32 v56, s44
	v_cmp_lt_i32_e32 vcc, s23, v198
	v_lshl_or_b32 v192, s72, 8, v226
	v_ashrrev_i32_e32 v193, 31, v192
	v_cndmask_b32_e32 v228, 0, v56, vcc
	v_mul_u32_u24_e32 v56, 0x1800, v228
	v_lshlrev_b32_e32 v96, 2, v56
	v_lshl_add_u64 v[56:57], s[70:71], 0, v[96:97]
	v_lshlrev_b64 v[68:69], 2, v[192:193]
	v_lshl_add_u64 v[124:125], v[56:57], 0, v[68:69]
	global_load_dwordx4 v[56:59], v[124:125], off
	v_cndmask_b32_e64 v70, 0, 1, s[78:79]
	v_cmp_ne_u32_e64 s[46:47], 1, v70
	s_andn2_b64 vcc, exec, s[78:79]
	v_lshl_add_u64 v[196:197], s[54:55], 0, v[68:69]
	s_cbranch_vccnz .LBB0_1024
	global_load_dwordx4 v[80:83], v[196:197], off
	s_waitcnt vmcnt(0)
	v_pk_mul_f32 v[58:59], v[58:59], v[82:83]
	v_pk_mul_f32 v[56:57], v[56:57], v[80:81]
